# x9a: as v13 plus removed canonicalizing v_max ops, waves 4-7 skip duplicate K2 staging, both MLA loop bodies 256B-aligned
# baseline (speedup 1.0000x reference)
; __device__ __forceinline__ int fresh_tid() { int t = threadIdx.x; asm volatile("" : "+v"(t)); return t; }
; __device__ __forceinline__ int v_st(int k, int c) { const int kk = (k & ~0xC) | ((k & 4) << 1) | ((k & 8) >> 1); return ((kk >> 3) * 4 + (c >> 5)) * 512 + ((kk & 7) * 32 + (c & 31)) * 2; }
; __device__ __forceinline__ int v_rd_base(int lane) { return ((lane & 3) << 3) | (((lane >> 2) & 3) << 6) | (((lane >> 4) & 1) << 5) | (((lane >> 5) & 1) << 8); }
; #define SLOAD(i, j) do { const long kr_ = KROW(j); sr_[i].vs0 = ld8(Vp + (kr_ + sr) * ldv + sc); sr_[i].ks0 = ld8(Kp + (kr_ + sr) * ldk + sc); \
;     if (DQK == 96) sr_[i].ks1 = ld8(Kp + (kr_ + sr2) * ldk + sc2); } while (0)
; #define SWRITE(b, i) do { *(bf16x8*)(V_lds + (b) * SHM_V + vst0) = sr_[i].vs0; *(bf16x8*)(K_lds + (b) * SHM_K + kst0) = sr_[i].ks0; \
;     if (DQK == 96) *(bf16x8*)(K_lds + (b) * SHM_K + kst1) = sr_[i].ks1; } while (0)
; template <int DQK, int MODE, int ldq, int ldk, int ldv> ...
;     ...
;   const int tid = fresh_tid(), wid = tid >> 6, lane = tid & 63, r32 = lane & 31, hi = lane >> 5;
;   char* V_lds = lds; char* K_lds = lds + 2 * SHM_V;
;   float* ws = (float*)(lds + 2 * SHM_V + 2 * SHM_K) + wid * 64; float* li_l = ws; float* al_l = ws + 32;
;   float m_reg = -1e30f, l_reg = 0; f32x16 o[2] = {}; bf16x8 qr[DQK / 16];
;   const bf16_t* Qw = Qb + (long)(wid * QBLK + r32) * ldq + hi * 8;
; #pragma unroll
;   for (int d0 = 0; d0 < DQK / 16; ++d0) qr[d0] = ld8(Qw + d0 * 16);
;   NaInfo na; na.brow = (const float*)(lds + rpb_off); na.qr = r0 + (wid >> 1); na.qc = (wid & 1) * 32 + r32;
;   const int sr = tid >> 3, sc = (tid & 7) * 8, vst0 = v_st(sr, sc), kst0 = KSWZ(sr, sc * 2);
;   const int sr2 = (tid & 255) >> 2, sc2 = 64 + (tid & 3) * 8, kst1 = KSWZ(sr2, sc2 * 2);
;   const int vb0 = (int)(uintptr_t)V_lds + v_rd_base(lane);
;   struct { bf16x8 vs0, ks0, ks1; } sr_[2];
;     ...
;   f32x16 pA0, pA1, pB0, pB1; float mnA, mnB, alA, alB; bf16x8 pa0, pa1, pa2, pa3;
;   constexpr int SE = 0, SO = 1;
;   SLOAD(SE, 0); SLOAD(SO, 1); asm volatile("s_waitcnt vmcnt(0)" ::: "memory"); SWRITE(0, SE); SWRITE(1, SO);
;   if (2 < NT) SLOAD(SE, 2);
;   __syncthreads();
.LBB0_299:
	v_readfirstlane_b32 s32, v234
	s_nop 0
	s_lshr_b32 s32, s32, 8
	s_ashr_i32 s11, s22, 7
	s_lshl_b32 s0, s22, 8
	s_lshl_b32 s10, s11, 13
	s_and_b32 s0, s0, 0x1f00
	s_or_b32 s6, s10, s0
	s_bfe_u32 s4, s22, 0x20005
	s_ashr_i32 s7, s6, 31
	s_mul_i32 s1, s6, 0x300
	s_mul_hi_i32 s0, s6, 0x300
	s_add_u32 s1, s16, s1
	s_addc_u32 s0, s17, s0
	s_mul_i32 s5, s4, 0xc0
	s_add_u32 s12, s1, s5
	s_addc_u32 s13, s0, 0
	s_add_u32 s0, s18, s5
	s_addc_u32 s1, s19, 0
	s_lshl_b32 s23, s4, 6
	s_lshl_b32 s4, s4, 7
	s_add_u32 s4, s20, s4
	s_addc_u32 s5, s21, 0
	s_lshl_b32 s24, s11, 8
	s_add_i32 s24, s24, 0x8000
	v_mov_b32_e32 v52, v234
	s_add_i32 s26, 0, 0x10000
	s_cmp_lg_u32 0, -1
	v_ashrrev_i32_e32 v130, 3, v52
	v_lshlrev_b32_e32 v28, 3, v52
	v_and_b32_e32 v0, 56, v28
	v_bfe_u32 v132, v52, 2, 6
	s_cselect_b32 s25, 0, 0
	s_ashr_i32 s11, s10, 31
	v_ashrrev_i32_e32 v131, 31, v130
	s_waitcnt lgkmcnt(0)
	v_lshlrev_b32_e32 v48, 1, v0
	v_lshl_add_u64 v[0:1], v[130:131], 0, s[10:11]
	v_mov_b64_e32 v[24:25], s[0:1]
	v_or_b32_e32 v8, s10, v132
	v_mad_u64_u32 v[4:5], s[28:29], v0, s70, v[24:25]
	v_mad_i64_i32 v[8:9], s[28:29], v8, s70, v[24:25]
	s_or_b32 s28, s10, 64
	s_ashr_i32 s29, s28, 31
	v_lshl_add_u64 v[16:17], v[130:131], 0, s[28:29]
	v_lshlrev_b64 v[2:3], 9, v[0:1]
	v_mad_u64_u32 v[18:19], s[30:31], v16, s70, v[24:25]
	v_lshl_add_u64 v[2:3], s[4:5], 0, v[2:3]
	v_mov_b32_e32 v49, v205
	v_mad_i32_i24 v5, v1, s70, v5
	v_mad_i32_i24 v19, v17, s70, v19
	v_lshlrev_b32_e32 v53, 4, v52
	v_lshl_add_u64 v[2:3], v[2:3], 0, v[48:49]
	v_lshl_add_u64 v[4:5], v[4:5], 0, v[48:49]
	v_lshlrev_b64 v[10:11], 9, v[16:17]
	v_lshl_add_u64 v[16:17], v[18:19], 0, v[48:49]
	v_or_b32_e32 v18, s28, v132
	v_and_b32_e32 v50, 48, v53
	global_load_dwordx4 v[0:3], v[2:3], off
	s_nop 0
	global_load_dwordx4 v[4:7], v[4:5], off
	v_mov_b32_e32 v51, v205
	v_lshl_add_u64 v[10:11], s[4:5], 0, v[10:11]
	v_mad_i64_i32 v[18:19], s[28:29], v18, s70, v[24:25]
	v_lshl_add_u64 v[8:9], v[8:9], 0, v[50:51]
	v_lshl_add_u64 v[12:13], v[10:11], 0, v[48:49]
	v_lshl_add_u64 v[20:21], v[18:19], 0, v[50:51]
	global_load_dwordx4 v[8:11], v[8:9], off offset:128
	s_nop 0
	global_load_dwordx4 v[12:15], v[12:13], off
	s_nop 0
	global_load_dwordx4 v[16:19], v[16:17], off
	s_nop 0
	global_load_dwordx4 v[20:23], v[20:21], off offset:128
	v_ashrrev_i32_e32 v54, 1, v52
	s_movk_i32 s11, 0xffe0
	v_bfe_u32 v133, v52, 5, 1
	v_bfi_b32 v29, s11, v54, v52
	v_mov_b64_e32 v[26:27], s[12:13]
	v_mad_i64_i32 v[26:27], s[12:13], v29, s70, v[26:27]
	v_lshlrev_b32_e32 v204, 4, v133
	v_lshl_add_u64 v[26:27], v[26:27], 0, v[204:205]
	global_load_dwordx4 v[84:87], v[26:27], off
	global_load_dwordx4 v[80:83], v[26:27], off offset:32
	global_load_dwordx4 v[76:79], v[26:27], off offset:64
	global_load_dwordx4 v[72:75], v[26:27], off offset:96
	global_load_dwordx4 v[68:71], v[26:27], off offset:128
	global_load_dwordx4 v[64:67], v[26:27], off offset:160
	v_and_b32_e32 v26, 0xfffff0, v130
	v_lshlrev_b32_e32 v27, 1, v130
	v_and_or_b32 v26, v27, 8, v26
	v_lshrrev_b32_e32 v26, 1, v26
	v_bfe_u32 v28, v28, 5, 1
	v_lshrrev_b32_e32 v27, 1, v130
	v_or_b32_e32 v26, v26, v28
	v_and_b32_e32 v28, 3, v130
	v_and_or_b32 v27, v27, 4, v28
	v_and_b32_e32 v28, 48, v48
	v_lshl_or_b32 v27, v27, 6, v28
	v_lshlrev_b32_e32 v28, 4, v130
	v_lshl_or_b32 v26, v26, 9, v27
	v_lshlrev_b32_e32 v27, 8, v130
	v_and_b32_e32 v28, 0xf0, v28
	s_or_b32 s12, s10, 0x80
	v_bitop3_b32 v27, v48, v27, v28 bitop3:0xde
	v_lshlrev_b32_e32 v30, 2, v52
	v_add_u32_e32 v145, 0, v26
	s_ashr_i32 s13, s12, 31
	v_lshlrev_b32_e32 v28, 8, v132
	v_or_b32_e32 v29, 0x80, v50
	v_and_b32_e32 v30, 0xf0, v30
	s_waitcnt vmcnt(0)
	v_add_u32_e32 v146, 0, v27
	v_bitop3_b32 v28, v29, v28, v30 bitop3:0xde
	v_add_u32_e32 v147, 0, v28
	v_and_b32_e32 v140, 31, v52
	v_and_b32_e32 v56, 63, v52
	v_and_b32_e32 v128, 0xffffffe0, v54
	v_readlane_b32 s76, v255, 19
	v_readlane_b32 s77, v255, 20
	v_readlane_b32 s78, v255, 21
	v_readlane_b32 s79, v255, 22
	v_readlane_b32 s80, v255, 23
	v_readlane_b32 s81, v255, 24
	v_readlane_b32 s82, v255, 25
	v_readlane_b32 s83, v255, 26
	v_readlane_b32 s84, v255, 27
	v_readlane_b32 s85, v255, 28
	v_readlane_b32 s86, v255, 29
	v_readlane_b32 s87, v255, 30
	v_readlane_b32 s88, v255, 31
	v_readlane_b32 s89, v255, 32
	v_readlane_b32 s90, v255, 33
	v_readlane_b32 s91, v255, 34
	s_mov_b32 s76, s77
	s_mov_b32 s78, s77
	s_mov_b32 s79, s77
	s_mov_b32 s80, s77
	s_mov_b32 s81, s77
	s_mov_b32 s82, s77
	s_mov_b32 s83, s77
	s_mov_b32 s84, s77
	s_mov_b32 s85, s77
	s_mov_b32 s86, s77
	s_mov_b32 s87, s77
	s_mov_b32 s88, s77
	s_waitcnt vmcnt(0)
	ds_write_b128 v145, v[0:3]
	v_lshl_add_u64 v[0:1], v[130:131], 0, s[12:13]
	ds_write_b128 v146, v[4:7] offset:32768
	v_lshlrev_b64 v[2:3], 9, v[0:1]
	v_mad_u64_u32 v[4:5], s[28:29], v0, s70, v[24:25]
	v_lshl_add_u64 v[2:3], s[4:5], 0, v[2:3]
	v_mad_i32_i24 v5, v1, s70, v5
	ds_write_b128 v147, v[8:11] offset:32768
	ds_write_b128 v145, v[12:15] offset:16384
	ds_write_b128 v146, v[16:19] offset:49152
	ds_write_b128 v147, v[20:23] offset:49152
	v_lshl_add_u64 v[2:3], v[2:3], 0, v[48:49]
	s_mov_b32 s98, 0xffff8000
	s_mov_b32 s99, -1
	v_lshl_add_u64 v[2:3], v[2:3], 0, s[98:99]
	v_lshl_add_u64 v[0:1], v[4:5], 0, v[48:49]
	global_load_dwordx4 v[92:95], v[2:3], off
	global_load_dwordx4 v[88:91], v[0:1], off
	v_or_b32_e32 v0, s12, v132
	v_mad_i64_i32 v[0:1], s[12:13], v0, s70, v[24:25]
	v_lshl_add_u64 v[0:1], v[0:1], 0, v[50:51]
	v_lshlrev_b32_e32 v8, 8, v140
	v_and_b32_e32 v9, 0xf0, v53
	global_load_dwordx4 v[96:99], v[0:1], off offset:128
	v_bitop3_b32 v0, v204, v8, v9 bitop3:0xde
	v_add_u32_e32 v148, 0, v0
	s_waitcnt lgkmcnt(0)
	s_barrier
; template <int DQK> __device__ __forceinline__ void partialSM(f32x16& p0, f32x16& p1, float& m_reg, float& mn, float& alpha) {
;   constexpr float SCALE = (DQK == 96) ? 0.10206207261596577f : 0.125f;
;   constexpr float C = SCALE * 1.4426950408889634f;
;   float pmax = p0[0];
; #pragma unroll
;   for (int r = 1; r < 16; ++r) pmax = fmaxf(pmax, p0[r]);
; #pragma unroll
;   for (int r = 0; r < 16; ++r) pmax = fmaxf(pmax, p1[r]);
;   { auto rr = __builtin_amdgcn_permlane32_swap(__float_as_uint(pmax), __float_as_uint(pmax), false, false);
;     pmax = fmaxf(__uint_as_float(rr[0]), __uint_as_float(rr[1])); }
;   if (__builtin_expect(__all(pmax - m_reg <= THR / SCALE), 1)) { mn = m_reg; alpha = 1.f; }
;   else { mn = fmaxf(m_reg, pmax); alpha = __builtin_amdgcn_exp2f((m_reg - mn) * C); m_reg = mn; }
;   float mnC = -mn * C;
; #pragma unroll
;   for (int r = 0; r < 16; ++r) p0[r] = fmaf(p0[r], C, mnC);
; #pragma unroll
;   for (int r = 0; r < 16; ++r) p1[r] = fmaf(p1[r], C, mnC);
; #pragma unroll
;   for (int r = 0; r < 16; ++r) p0[r] = __builtin_amdgcn_exp2f(p0[r]);
; }
; template <int DQK> __device__ __forceinline__ void qkt(f32x16& p0, f32x16& p1, const char* Ks, const bf16x8* qr, int r32, int hi) {
;   p0 = f32x16{}; p1 = f32x16{};
; #pragma unroll
;   for (int d0 = 0; d0 < DQK / 16; ++d0) { int cb = (d0 * 16 + hi * 8) * 2;
;     bf16x8 b0 = *reinterpret_cast<const bf16x8*>(Ks + KSWZ(r32, cb));
;     bf16x8 b1 = *reinterpret_cast<const bf16x8*>(Ks + KSWZ(32 + r32, cb));
;     p0 = __builtin_amdgcn_mfma_f32_32x32x16_bf16(b0, qr[d0], p0, 0, 0, 0);
;     p1 = __builtin_amdgcn_mfma_f32_32x32x16_bf16(b1, qr[d0], p1, 0, 0, 0); }
; }
	ds_read_b128 v[0:3], v148 offset:32768
	ds_read_b128 v[4:7], v148 offset:40960
	s_waitcnt lgkmcnt(1)
	v_mfma_f32_32x32x16_bf16 v[32:47], v[0:3], v[84:87], 0
	v_or_b32_e32 v0, 32, v204
	v_bitop3_b32 v0, v0, v8, v9 bitop3:0xde
	v_add_u32_e32 v152, 0, v0
	v_lshlrev_b32_e32 v10, 3, v56
	v_and_b32_e32 v11, 0xc0, v53
	s_mov_b32 s89, s77
	s_mov_b32 s90, s77
	s_waitcnt lgkmcnt(0)
	v_mfma_f32_32x32x16_bf16 v[16:31], v[4:7], v[84:87], 0
	ds_read_b128 v[0:3], v152 offset:32768
	ds_read_b128 v[4:7], v152 offset:40960
	s_mov_b32 s91, s77
	v_lshl_add_u64 v[134:135], s[4:5], 0, v[48:49]
	v_lshl_add_u64 v[136:137], s[0:1], 0, v[48:49]
	s_mov_b32 s13, s77
	s_mov_b32 s11, 4
	v_lshl_add_u64 v[138:139], s[0:1], 0, v[50:51]
	s_waitcnt lgkmcnt(1)
	v_mfma_f32_32x32x16_bf16 v[32:47], v[0:3], v[80:83], v[32:47]
	v_or_b32_e32 v0, 64, v204
	v_bitop3_b32 v0, v0, v8, v9 bitop3:0xde
	v_add_u32_e32 v151, 0, v0
	v_cmp_gt_u32_e64 s[4:5], 32, v56
	v_mov_b32_e32 v142, 0
	s_waitcnt lgkmcnt(0)
	v_mfma_f32_32x32x16_bf16 v[16:31], v[4:7], v[80:83], v[16:31]
	ds_read_b128 v[0:3], v151 offset:32768
	ds_read_b128 v[4:7], v151 offset:40960
	s_waitcnt lgkmcnt(1)
	v_mfma_f32_32x32x16_bf16 v[32:47], v[0:3], v[76:79], v[32:47]
	v_or_b32_e32 v0, 0x60, v204
	v_bitop3_b32 v0, v0, v8, v9 bitop3:0xde
	v_add_u32_e32 v149, 0, v0
	ds_read_b128 v[0:3], v149 offset:32768
	s_waitcnt lgkmcnt(1)
	v_mfma_f32_32x32x16_bf16 v[16:31], v[4:7], v[76:79], v[16:31]
	v_and_b32_e32 v4, 0x3fffffc0, v52
	v_lshl_add_u32 v57, v4, 2, s26
	ds_read_b128 v[4:7], v149 offset:40960
	v_lshl_add_u32 v141, v140, 2, v57
	v_add_u32_e32 v129, v57, v204
	s_waitcnt lgkmcnt(1)
	v_mfma_f32_32x32x16_bf16 v[32:47], v[0:3], v[72:75], v[32:47]
	v_or_b32_e32 v0, 0x80, v204
	v_bitop3_b32 v0, v0, v8, v9 bitop3:0xde
	v_add_u32_e32 v150, 0, v0
	ds_read_b128 v[0:3], v150 offset:32768
	s_waitcnt lgkmcnt(1)
	v_mfma_f32_32x32x16_bf16 v[16:31], v[4:7], v[72:75], v[16:31]
	v_lshlrev_b32_e32 v5, 1, v52
	v_and_or_b32 v4, v10, 24, v11
	v_and_b32_e32 v5, 32, v5
	v_and_b32_e32 v6, 0x100, v10
	v_or3_b32 v58, v4, v5, v6
	ds_read_b128 v[4:7], v150 offset:40960
	v_add_u32_e32 v144, s25, v58
	s_waitcnt lgkmcnt(1)
	v_mfma_f32_32x32x16_bf16 v[32:47], v[0:3], v[68:71], v[32:47]
	v_or_b32_e32 v0, 0xa0, v204
	v_bitop3_b32 v0, v0, v8, v9 bitop3:0xde
	v_add_u32_e32 v153, 0, v0
	ds_read_b128 v[0:3], v153 offset:32768
	ds_read_b128 v[52:55], v153 offset:40960
	v_writelane_b32 v255, s12, 19
	s_waitcnt lgkmcnt(2)
	v_mfma_f32_32x32x16_bf16 v[16:31], v[4:7], v[68:71], v[16:31]
	v_writelane_b32 v255, s13, 20
	v_writelane_b32 v255, s14, 21
	v_writelane_b32 v255, s15, 22
	v_writelane_b32 v255, s16, 23
	v_writelane_b32 v255, s17, 24
	v_writelane_b32 v255, s18, 25
	v_writelane_b32 v255, s19, 26
	s_waitcnt lgkmcnt(1)
	v_mfma_f32_32x32x16_bf16 v[32:47], v[0:3], v[64:67], v[32:47]
	v_mov_b64_e32 v[0:1], s[76:77]
	v_mov_b64_e32 v[2:3], s[78:79]
	v_mov_b64_e32 v[4:5], s[80:81]
	v_mov_b64_e32 v[6:7], s[82:83]
	v_mov_b64_e32 v[8:9], s[84:85]
	v_mov_b64_e32 v[10:11], s[86:87]
	v_mov_b64_e32 v[12:13], s[88:89]
	s_waitcnt lgkmcnt(0)
	v_mfma_f32_32x32x16_bf16 v[16:31], v[52:55], v[64:67], v[16:31]
	s_nop 2
	v_max_f32_e32 v52, v33, v33
	v_max_f32_e32 v53, v32, v32
	v_max_f32_e32 v52, v53, v52
	v_max3_f32 v52, v52, v34, v35
	v_max3_f32 v52, v52, v36, v37
	v_max3_f32 v52, v52, v38, v39
	v_max3_f32 v52, v52, v40, v41
	v_max3_f32 v52, v52, v42, v43
	v_max3_f32 v52, v52, v44, v45
	v_max3_f32 v52, v52, v46, v47
	v_max3_f32 v52, v52, v16, v17
	v_max3_f32 v52, v52, v18, v19
	v_max3_f32 v52, v52, v20, v21
	v_max3_f32 v52, v52, v22, v23
	v_max3_f32 v52, v52, v24, v25
	v_max3_f32 v52, v52, v26, v27
	v_max3_f32 v52, v52, v28, v29
	v_max3_f32 v52, v52, v30, v31
	v_mov_b32_e32 v53, v52
	s_nop 1
	v_permlane32_swap_b32_e32 v52, v53
	v_max_f32_e32 v53, v53, v53
	v_max_f32_e32 v52, v52, v52
	v_max_f32_e32 v52, v52, v53
	v_mov_b64_e32 v[14:15], s[90:91]
	s_mov_b32 s80, 0x429cc470
	v_add_f32_e32 v53, 0x7149f2ca, v52
	v_cmp_ge_f32_e32 vcc, s80, v53
	s_cmp_eq_u64 vcc, exec
	v_max_f32_e32 v49, 0xf149f2ca, v52
	s_cselect_b64 vcc, -1, 0
	v_cndmask_b32_e32 v116, v49, v248, vcc
	v_mul_f32_e32 v48, 0xbe16c740, v116
	v_fmamk_f32 v32, v32, 0x3e16c740, v48
	v_exp_f32_e32 v126, v32
	v_fmamk_f32 v32, v33, 0x3e16c740, v48
	v_exp_f32_e32 v160, v32
	v_fmamk_f32 v32, v34, 0x3e16c740, v48
	v_exp_f32_e32 v127, v32
	v_fmamk_f32 v32, v35, 0x3e16c740, v48
	v_exp_f32_e32 v161, v32
	v_fmamk_f32 v32, v36, 0x3e16c740, v48
	v_exp_f32_e32 v158, v32
	v_fmamk_f32 v32, v37, 0x3e16c740, v48
	v_exp_f32_e32 v162, v32
	v_fmamk_f32 v32, v38, 0x3e16c740, v48
	v_exp_f32_e32 v159, v32
	v_fmamk_f32 v32, v39, 0x3e16c740, v48
	v_writelane_b32 v255, s20, 27
	v_exp_f32_e32 v163, v32
	v_fmamk_f32 v32, v40, 0x3e16c740, v48
	v_writelane_b32 v255, s21, 28
	v_exp_f32_e32 v118, v32
	v_fmamk_f32 v32, v41, 0x3e16c740, v48
	v_writelane_b32 v255, s22, 29
	v_exp_f32_e32 v121, v32
	v_fmamk_f32 v32, v42, 0x3e16c740, v48
	v_sub_f32_e32 v33, 0xf149f2ca, v49
	v_writelane_b32 v255, s23, 30
	v_exp_f32_e32 v119, v32
	v_fmamk_f32 v32, v43, 0x3e16c740, v48
	v_mul_f32_e32 v33, 0x3e16c740, v33
	v_writelane_b32 v255, s24, 31
	v_exp_f32_e32 v122, v32
	v_fmamk_f32 v32, v44, 0x3e16c740, v48
	v_exp_f32_e32 v33, v33
	v_writelane_b32 v255, s25, 32
	v_exp_f32_e32 v120, v32
	v_fmamk_f32 v32, v45, 0x3e16c740, v48
	v_writelane_b32 v255, s26, 33
	v_exp_f32_e32 v123, v32
	v_fmamk_f32 v32, v46, 0x3e16c740, v48
	v_writelane_b32 v255, s27, 34
	v_exp_f32_e32 v124, v32
	v_fmamk_f32 v32, v47, 0x3e16c740, v48
	v_pk_fma_f32 v[100:101], v[30:31], s[40:41], v[48:49] op_sel_hi:[1,0,0]
	v_pk_fma_f32 v[106:107], v[28:29], s[40:41], v[48:49] op_sel_hi:[1,0,0]
	v_pk_fma_f32 v[110:111], v[26:27], s[40:41], v[48:49] op_sel_hi:[1,0,0]
	v_pk_fma_f32 v[102:103], v[24:25], s[40:41], v[48:49] op_sel_hi:[1,0,0]
	v_pk_fma_f32 v[104:105], v[22:23], s[40:41], v[48:49] op_sel_hi:[1,0,0]
	v_pk_fma_f32 v[108:109], v[20:21], s[40:41], v[48:49] op_sel_hi:[1,0,0]
	v_pk_fma_f32 v[112:113], v[18:19], s[40:41], v[48:49] op_sel_hi:[1,0,0]
	v_pk_fma_f32 v[114:115], v[16:17], s[40:41], v[48:49] op_sel_hi:[1,0,0]
	s_addk_i32 s25, 0x4000
	v_mov_b64_e32 v[30:31], v[14:15]
	s_mov_b64 s[84:85], 0x90000
	s_movk_i32 s83, 0x6000
	s_movk_i32 s82, 0x100
	v_readlane_b32 s89, v255, 47
	v_readlane_b32 s76, v255, 37
	s_movk_i32 s90, 0x1fff
	s_mov_b32 s88, 0x42800000
	s_movk_i32 s87, 0x7000
	s_movk_i32 s86, 0x1200
	s_movk_i32 s81, 0x5000
	s_movk_i32 s78, 0x4000
	v_exp_f32_e32 v125, v32
	v_cndmask_b32_e64 v154, v33, 1.0, vcc
	v_add_u32_e32 v143, s25, v58
	v_mov_b64_e32 v[28:29], v[12:13]
	v_mov_b64_e32 v[26:27], v[10:11]
	v_mov_b64_e32 v[24:25], v[8:9]
	v_mov_b64_e32 v[22:23], v[6:7]
	v_mov_b64_e32 v[20:21], v[4:5]
	v_mov_b64_e32 v[18:19], v[2:3]
	v_mov_b64_e32 v[16:17], v[0:1]
	s_barrier
	.p2align 8
; #define SBAR() __builtin_amdgcn_sched_barrier(0)
; #define SLOAD(i, j) do { const long kr_ = KROW(j); sr_[i].vs0 = ld8(Vp + (kr_ + sr) * ldv + sc); sr_[i].ks0 = ld8(Kp + (kr_ + sr) * ldk + sc); \
;     if (DQK == 96) sr_[i].ks1 = ld8(Kp + (kr_ + sr2) * ldk + sc2); } while (0)
; #define SWRITE(b, i) do { *(bf16x8*)(V_lds + (b) * SHM_V + vst0) = sr_[i].vs0; *(bf16x8*)(K_lds + (b) * SHM_K + kst0) = sr_[i].ks0; \
;     if (DQK == 96) *(bf16x8*)(K_lds + (b) * SHM_K + kst1) = sr_[i].ks1; } while (0)
; #define BIAS(P0, P1, j) do { if (MODE == 1) { SBAR(); if ((j) >= nA) na_bias(P0, P1, na, rs0 + (j) - nA, hi); SBAR(); } } while (0)
; __device__ __forceinline__ void finishSM(f32x16& p0, f32x16& p1, float alpha, float& l_reg, bf16x8& pa0, bf16x8& pa1, bf16x8& pa2, bf16x8& pa3) {
; #pragma unroll
;   for (int r = 0; r < 16; ++r) p1[r] = __builtin_amdgcn_exp2f(p1[r]);
;   float ps = 0;
; #pragma unroll
;   for (int r = 0; r < 16; ++r) ps += p0[r];
; #pragma unroll
;   for (int r = 0; r < 16; ++r) ps += p1[r];
;   { auto rr = __builtin_amdgcn_permlane32_swap(__float_as_uint(ps), __float_as_uint(ps), false, false);
;     ps = __uint_as_float(rr[0]) + __uint_as_float(rr[1]); }
;   l_reg = l_reg * alpha + ps;
;     ...
;   PK4(p0, 0, pa0); PK4(p0, 8, pa1); PK4(p1, 0, pa2); PK4(p1, 8, pa3);
;     ...
; }
; template <int DQK> __device__ __forceinline__ void qkt(f32x16& p0, f32x16& p1, const char* Ks, const bf16x8* qr, int r32, int hi) {
;   p0 = f32x16{}; p1 = f32x16{};
; #pragma unroll
;   for (int d0 = 0; d0 < DQK / 16; ++d0) { int cb = (d0 * 16 + hi * 8) * 2;
;     bf16x8 b0 = *reinterpret_cast<const bf16x8*>(Ks + KSWZ(r32, cb));
;     bf16x8 b1 = *reinterpret_cast<const bf16x8*>(Ks + KSWZ(32 + r32, cb));
;     p0 = __builtin_amdgcn_mfma_f32_32x32x16_bf16(b0, qr[d0], p0, 0, 0, 0);
;     p1 = __builtin_amdgcn_mfma_f32_32x32x16_bf16(b1, qr[d0], p1, 0, 0, 0); }
; }
; template <int DQK, int MODE, int ldq, int ldk, int ldv> ...
;     ...
;   for (int j = 1; j + 1 < NT; j += 2) {
;     SBAR(); qkt<DQK>(pB0, pB1, K_lds + SHM_K, qr, r32, hi);
;     finishSM(pA0, pA1, alA, l_reg, pa0, pa1, pa2, pa3); SBAR();
;     SLOAD(SO, j + 2); SBAR();
;     pv_d0(o, vb0, pa0, pa1, pa2, pa3); BIAS(pB0, pB1, j); partialSM<DQK>(pB0, pB1, m_reg, mnB, alB);
;     __syncthreads(); SWRITE(0, SE);
;     RESC(alB); __syncthreads();
.LBB0_300:
	s_add_i32 s25, s11, -3
	s_cmp_lg_u32 s32, 0
	s_cbranch_scc1 .Lmy_h1B
	ds_read_b128 v[32:35], v148 offset:49152
	ds_read_b128 v[36:39], v148 offset:57344
	ds_read_b128 v[164:167], v152 offset:49152
	ds_read_b128 v[168:171], v152 offset:57344
	v_exp_f32_e32 v117, v114
	v_exp_f32_e32 v157, v115
	s_waitcnt lgkmcnt(3)
	v_mfma_f32_32x32x16_bf16 v[48:63], v[32:35], v[84:87], 0
	v_exp_f32_e32 v108, v108
	v_exp_f32_e32 v109, v109
	v_exp_f32_e32 v104, v104
	v_exp_f32_e32 v105, v105
	v_exp_f32_e32 v102, v102
	v_exp_f32_e32 v103, v103
	v_exp_f32_e32 v110, v110
	s_waitcnt lgkmcnt(2)
	v_mfma_f32_32x32x16_bf16 v[32:47], v[36:39], v[84:87], 0
	v_exp_f32_e32 v111, v111
	v_exp_f32_e32 v106, v106
	v_exp_f32_e32 v107, v107
	v_exp_f32_e32 v100, v100
	v_exp_f32_e32 v101, v101
	s_waitcnt lgkmcnt(1)
	v_mfma_f32_32x32x16_bf16 v[48:63], v[164:167], v[80:83], v[48:63]
	s_waitcnt lgkmcnt(0)
	v_mfma_f32_32x32x16_bf16 v[32:47], v[168:171], v[80:83], v[32:47]
	ds_read_b128 v[164:167], v151 offset:49152
	ds_read_b128 v[168:171], v151 offset:57344
	s_waitcnt lgkmcnt(1)
	v_mfma_f32_32x32x16_bf16 v[48:63], v[164:167], v[76:79], v[48:63]
	s_waitcnt lgkmcnt(0)
	v_mfma_f32_32x32x16_bf16 v[32:47], v[168:171], v[76:79], v[32:47]
	ds_read_b128 v[164:167], v149 offset:49152
	ds_read_b128 v[168:171], v149 offset:57344
	s_waitcnt lgkmcnt(1)
	v_mfma_f32_32x32x16_bf16 v[48:63], v[164:167], v[72:75], v[48:63]
	s_waitcnt lgkmcnt(0)
	v_mfma_f32_32x32x16_bf16 v[32:47], v[168:171], v[72:75], v[32:47]
	ds_read_b128 v[164:167], v150 offset:49152
	ds_read_b128 v[168:171], v150 offset:57344
	s_waitcnt lgkmcnt(1)
	v_mfma_f32_32x32x16_bf16 v[48:63], v[164:167], v[68:71], v[48:63]
	s_waitcnt lgkmcnt(0)
	v_mfma_f32_32x32x16_bf16 v[32:47], v[168:171], v[68:71], v[32:47]
	ds_read_b128 v[164:167], v153 offset:49152
	ds_read_b128 v[168:171], v153 offset:57344
	s_waitcnt vmcnt(0)
	ds_write_b128 v146, v[88:91] offset:32768
	ds_write_b128 v147, v[96:99] offset:32768
	ds_write_b128 v145, v[92:95] offset:16384
	s_waitcnt lgkmcnt(4)
	v_mfma_f32_32x32x16_bf16 v[48:63], v[164:167], v[64:67], v[48:63]
	v_exp_f32_e32 v164, v112
	v_add_f32_e32 v112, 0, v126
	v_add_f32_e32 v112, v160, v112
	v_add_f32_e32 v112, v127, v112
	v_add_f32_e32 v112, v161, v112
	v_add_f32_e32 v112, v158, v112
	v_add_f32_e32 v112, v162, v112
	v_add_f32_e32 v112, v159, v112
	v_add_f32_e32 v112, v163, v112
	v_add_f32_e32 v112, v118, v112
	v_add_f32_e32 v112, v121, v112
	v_add_f32_e32 v112, v119, v112
	v_add_f32_e32 v112, v122, v112
	v_add_f32_e32 v112, v120, v112
	v_add_f32_e32 v112, v123, v112
	v_add_f32_e32 v112, v124, v112
	v_exp_f32_e32 v165, v113
	v_add_f32_e32 v112, v125, v112
	v_add_f32_e32 v112, v117, v112
	v_add_f32_e32 v112, v157, v112
	v_add_f32_e32 v112, v164, v112
	v_add_f32_e32 v112, v165, v112
	v_add_f32_e32 v112, v108, v112
	v_add_f32_e32 v112, v109, v112
	v_add_f32_e32 v112, v104, v112
	v_add_f32_e32 v112, v105, v112
	v_add_f32_e32 v112, v102, v112
	v_add_f32_e32 v112, v103, v112
	s_waitcnt lgkmcnt(3)
	v_mfma_f32_32x32x16_bf16 v[32:47], v[168:171], v[64:67], v[32:47]
	ds_read_b64_tr_b16 v[192:193], v144 offset:0
	ds_read_b64_tr_b16 v[194:195], v144 offset:0x800
	ds_read_b64_tr_b16 v[196:197], v144 offset:0x1000
	ds_read_b64_tr_b16 v[198:199], v144 offset:0x1800
	ds_read_b64_tr_b16 v[200:201], v144 offset:0x2000
	ds_read_b64_tr_b16 v[202:203], v144 offset:0x2800
	ds_read_b64_tr_b16 v[210:211], v144 offset:0x3000
	ds_read_b64_tr_b16 v[212:213], v144 offset:0x3800
	v_add_f32_e32 v112, v110, v112
	v_add_f32_e32 v112, v111, v112
	v_add_f32_e32 v112, v106, v112
	v_add_f32_e32 v112, v107, v112
	v_add_f32_e32 v112, v100, v112
	v_add_f32_e32 v155, v101, v112
	v_mov_b32_e32 v156, v155
	v_cvt_pk_bf16_f32 v214, v126, v160
	v_cvt_pk_bf16_f32 v215, v127, v161
	v_cvt_pk_bf16_f32 v216, v158, v162
	s_nop 1
	v_permlane32_swap_b32_e32 v155, v156
	v_cvt_pk_bf16_f32 v217, v159, v163
	v_permlane32_swap_b32_e32 v214, v216
	v_cvt_pk_bf16_f32 v218, v118, v121
	v_cvt_pk_bf16_f32 v219, v119, v122
	v_cvt_pk_bf16_f32 v220, v120, v123
	v_cvt_pk_bf16_f32 v221, v124, v125
	v_cvt_pk_bf16_f32 v222, v117, v157
	v_cvt_pk_bf16_f32 v223, v164, v165
	v_cvt_pk_bf16_f32 v224, v108, v109
	v_cvt_pk_bf16_f32 v225, v104, v105
	v_cvt_pk_bf16_f32 v226, v102, v103
	v_cvt_pk_bf16_f32 v227, v110, v111
	v_cvt_pk_bf16_f32 v228, v106, v107
	v_cvt_pk_bf16_f32 v229, v100, v101
	v_permlane32_swap_b32_e32 v215, v217
	v_permlane32_swap_b32_e32 v218, v220
	v_permlane32_swap_b32_e32 v219, v221
	v_permlane32_swap_b32_e32 v222, v224
	v_permlane32_swap_b32_e32 v223, v225
	v_permlane32_swap_b32_e32 v226, v228
	v_permlane32_swap_b32_e32 v227, v229
	s_cmpk_lt_u32 s25, 0x7e
	s_cselect_b32 s0, 0, 0xffffff80
	s_cselect_b32 s1, s10, s24
	s_add_i32 s0, s0, s11
	s_lshl_b32 s0, s0, 6
	s_add_i32 s0, s0, s1
	s_sub_i32 s0, s0, 64
	s_ashr_i32 s1, s0, 31
	s_cmpk_lt_u32 s25, 0x7f
	s_cselect_b32 s98, 0, 0xffffff80
	s_cselect_b32 s99, s10, s24
	s_add_i32 s98, s98, s11
	s_lshl_b32 s98, s98, 6
	s_add_i32 s98, s98, s99
	s_addk_i32 s98, 0xff80
	s_ashr_i32 s99, s98, 31
	v_lshl_add_u64 v[100:101], s[0:1], 0, v[130:131]
	v_lshl_add_u64 v[104:105], s[98:99], 0, v[130:131]
	v_lshlrev_b64 v[104:105], 9, v[104:105]
	v_lshl_add_u64 v[104:105], v[134:135], 0, v[104:105]
	v_mad_u64_u32 v[102:103], s[12:13], v100, s70, v[136:137]
	v_or_b32_e32 v106, s0, v132
	v_mad_i32_i24 v103, v101, s70, v103
	v_mad_i64_i32 v[106:107], s[0:1], v106, s70, v[138:139]
	global_load_dwordx4 v[184:187], v[102:103], off
	s_nop 0
	global_load_dwordx4 v[188:191], v[104:105], off
	s_nop 0
	global_load_dwordx4 v[230:233], v[106:107], off offset:128
	s_waitcnt lgkmcnt(0)
; #define SBAR() __builtin_amdgcn_sched_barrier(0)
; template <int DQK> __device__ __forceinline__ void partialSM(f32x16& p0, f32x16& p1, float& m_reg, float& mn, float& alpha) {
;   constexpr float SCALE = (DQK == 96) ? 0.10206207261596577f : 0.125f;
;   constexpr float C = SCALE * 1.4426950408889634f;
;   float pmax = p0[0];
; #pragma unroll
;   for (int r = 1; r < 16; ++r) pmax = fmaxf(pmax, p0[r]);
; #pragma unroll
;   for (int r = 0; r < 16; ++r) pmax = fmaxf(pmax, p1[r]);
;   { auto rr = __builtin_amdgcn_permlane32_swap(__float_as_uint(pmax), __float_as_uint(pmax), false, false);
;     pmax = fmaxf(__uint_as_float(rr[0]), __uint_as_float(rr[1])); }
;   if (__builtin_expect(__all(pmax - m_reg <= THR / SCALE), 1)) { mn = m_reg; alpha = 1.f; }
;   else { mn = fmaxf(m_reg, pmax); alpha = __builtin_amdgcn_exp2f((m_reg - mn) * C); m_reg = mn; }
;   float mnC = -mn * C;
; #pragma unroll
;   for (int r = 0; r < 16; ++r) p0[r] = fmaf(p0[r], C, mnC);
; #pragma unroll
;   for (int r = 0; r < 16; ++r) p1[r] = fmaf(p1[r], C, mnC);
; #pragma unroll
;   for (int r = 0; r < 16; ++r) p0[r] = __builtin_amdgcn_exp2f(p0[r]);
; }
; template <int D0> __device__ __forceinline__ void pv_one(f32x16& od, int vb, bf16x8 pa0, bf16x8 pa1, bf16x8 pa2, bf16x8 pa3) {
;   const s16x4 l0 = tr_read<v_rd_off(D0, 0, 0)>(vb), h0 = tr_read<v_rd_off(D0, 0, 1)>(vb), l1 = tr_read<v_rd_off(D0, 1, 0)>(vb), h1 = tr_read<v_rd_off(D0, 1, 1)>(vb);
;   const s16x4 l2 = tr_read<v_rd_off(D0, 2, 0)>(vb), h2 = tr_read<v_rd_off(D0, 2, 1)>(vb), l3 = tr_read<v_rd_off(D0, 3, 0)>(vb), h3 = tr_read<v_rd_off(D0, 3, 1)>(vb);
;   asm volatile("s_waitcnt lgkmcnt(0)" ::: "memory"); SBAR();
;   od = __builtin_amdgcn_mfma_f32_32x32x16_bf16(pa0, PKLH(l0, h0), od, 0, 0, 0);
;   od = __builtin_amdgcn_mfma_f32_32x32x16_bf16(pa1, PKLH(l1, h1), od, 0, 0, 0);
;   od = __builtin_amdgcn_mfma_f32_32x32x16_bf16(pa2, PKLH(l2, h2), od, 0, 0, 0);
;   od = __builtin_amdgcn_mfma_f32_32x32x16_bf16(pa3, PKLH(l3, h3), od, 0, 0, 0);
; }
; __device__ __forceinline__ void pv_d0(f32x16* o, int vb, bf16x8 pa0, bf16x8 pa1, bf16x8 pa2, bf16x8 pa3) {
;   pv_one<0>(o[0], vb, pa0, pa1, pa2, pa3); pv_one<1>(o[1], vb, pa0, pa1, pa2, pa3);
; }
	s_nop 0
	v_mfma_f32_32x32x16_bf16 v[0:15], v[214:217], v[192:195], v[0:15]
	ds_read_b64_tr_b16 v[192:193], v144 offset:0x200
	ds_read_b64_tr_b16 v[194:195], v144 offset:0xa00
	v_max_f32_e32 v112, v48, v49
	v_max3_f32 v112, v112, v50, v51
	v_max3_f32 v112, v112, v52, v53
	v_mfma_f32_32x32x16_bf16 v[0:15], v[218:221], v[196:199], v[0:15]
	ds_read_b64_tr_b16 v[196:197], v144 offset:0x1200
	ds_read_b64_tr_b16 v[198:199], v144 offset:0x1a00
	v_max3_f32 v112, v112, v54, v55
	v_max3_f32 v112, v112, v56, v57
	v_max3_f32 v112, v112, v58, v59
	v_max3_f32 v112, v112, v60, v61
	v_max3_f32 v112, v112, v62, v63
	v_mfma_f32_32x32x16_bf16 v[0:15], v[222:225], v[200:203], v[0:15]
	ds_read_b64_tr_b16 v[200:201], v144 offset:0x2200
	ds_read_b64_tr_b16 v[202:203], v144 offset:0x2a00
	v_max3_f32 v112, v112, v32, v33
	v_max3_f32 v112, v112, v34, v35
	v_max3_f32 v112, v112, v36, v37
	v_max3_f32 v112, v112, v38, v39
	v_max3_f32 v112, v112, v40, v41
	v_mfma_f32_32x32x16_bf16 v[0:15], v[226:229], v[210:213], v[0:15]
	ds_read_b64_tr_b16 v[210:211], v144 offset:0x3200
	ds_read_b64_tr_b16 v[212:213], v144 offset:0x3a00
	v_max3_f32 v112, v112, v42, v43
	v_max3_f32 v112, v112, v44, v45
	v_max3_f32 v112, v112, v46, v47
	v_mov_b32_e32 v113, v112
	s_nop 1
	v_permlane32_swap_b32_e32 v112, v113
	v_max_f32_e32 v112, v112, v113
	v_sub_f32_e32 v113, v112, v116
	v_cmp_ge_f32_e32 vcc, s80, v113
	v_max_f32_e32 v112, v116, v112
	s_waitcnt lgkmcnt(0)
	v_mfma_f32_32x32x16_bf16 v[16:31], v[214:217], v[192:195], v[16:31]
	v_sub_f32_e32 v113, v116, v112
	v_mul_f32_e32 v113, 0x3e16c740, v113
	v_exp_f32_e32 v113, v113
	s_cmp_eq_u64 vcc, exec
	s_cselect_b64 s[0:1], -1, 0
	v_cndmask_b32_e64 v157, v113, 1.0, s[0:1]
	v_cmp_gt_f32_e32 vcc, 1.0, v157
	v_cndmask_b32_e64 v158, v112, v116, s[0:1]
	v_mul_f32_e32 v159, 0xbe16c740, v158
	v_fmamk_f32 v48, v48, 0x3e16c740, v159
	v_fmamk_f32 v49, v49, 0x3e16c740, v159
	v_fmamk_f32 v50, v50, 0x3e16c740, v159
	v_fmamk_f32 v51, v51, 0x3e16c740, v159
	v_mfma_f32_32x32x16_bf16 v[16:31], v[218:221], v[196:199], v[16:31]
	v_fmamk_f32 v52, v52, 0x3e16c740, v159
	v_fmamk_f32 v53, v53, 0x3e16c740, v159
	v_fmamk_f32 v54, v54, 0x3e16c740, v159
	v_fmamk_f32 v55, v55, 0x3e16c740, v159
	v_fmamk_f32 v56, v56, 0x3e16c740, v159
	v_fmamk_f32 v57, v57, 0x3e16c740, v159
	v_fmamk_f32 v58, v58, 0x3e16c740, v159
	v_fmamk_f32 v59, v59, 0x3e16c740, v159
	v_fmamk_f32 v60, v60, 0x3e16c740, v159
	v_fmamk_f32 v61, v61, 0x3e16c740, v159
	v_mfma_f32_32x32x16_bf16 v[16:31], v[222:225], v[200:203], v[16:31]
	v_fmamk_f32 v62, v62, 0x3e16c740, v159
	v_fmamk_f32 v63, v63, 0x3e16c740, v159
	v_exp_f32_e32 v112, v48
	v_exp_f32_e32 v127, v49
	v_exp_f32_e32 v113, v50
	v_exp_f32_e32 v126, v51
	v_exp_f32_e32 v114, v52
	v_exp_f32_e32 v125, v53
	v_exp_f32_e32 v115, v54
	v_exp_f32_e32 v124, v55
	v_mfma_f32_32x32x16_bf16 v[16:31], v[226:229], v[210:213], v[16:31]
	v_exp_f32_e32 v116, v56
	v_exp_f32_e32 v123, v57
	v_exp_f32_e32 v117, v58
	v_exp_f32_e32 v122, v59
	v_exp_f32_e32 v118, v60
	v_exp_f32_e32 v121, v61
	v_exp_f32_e32 v119, v62
	v_exp_f32_e32 v120, v63
	v_fmamk_f32 v164, v42, 0x3e16c740, v159
	v_fmamk_f32 v165, v43, 0x3e16c740, v159
	v_fmamk_f32 v167, v32, 0x3e16c740, v159
	v_fmamk_f32 v168, v33, 0x3e16c740, v159
	v_fmamk_f32 v169, v34, 0x3e16c740, v159
	v_fmamk_f32 v170, v35, 0x3e16c740, v159
	v_fmamk_f32 v171, v36, 0x3e16c740, v159
	v_fmamk_f32 v172, v37, 0x3e16c740, v159
	v_fmamk_f32 v160, v38, 0x3e16c740, v159
	v_fmamk_f32 v161, v39, 0x3e16c740, v159
	v_fmamk_f32 v162, v40, 0x3e16c740, v159
	v_fmamk_f32 v163, v41, 0x3e16c740, v159
	v_fmamk_f32 v166, v44, 0x3e16c740, v159
	v_fmamk_f32 v173, v45, 0x3e16c740, v159
	v_fmamk_f32 v174, v46, 0x3e16c740, v159
	v_fmac_f32_e32 v159, 0x3e16c740, v47
	s_cbranch_vccz .LBB0_304
	s_and_saveexec_b64 s[12:13], s[4:5]
	ds_write_b32 v141, v157 offset:128
	s_or_b64 exec, exec, s[12:13]
	s_waitcnt lgkmcnt(0)
	ds_read_b128 v[192:195], v129 offset:224
	ds_read_b128 v[196:199], v129 offset:192
	ds_read_b128 v[200:203], v129 offset:160
	ds_read_b128 v[210:213], v129 offset:128
	s_waitcnt lgkmcnt(3)
	v_pk_mul_f32 v[14:15], v[14:15], v[194:195]
	s_waitcnt lgkmcnt(2)
	v_pk_mul_f32 v[10:11], v[10:11], v[198:199]
	s_waitcnt lgkmcnt(1)
	v_pk_mul_f32 v[6:7], v[6:7], v[202:203]
	s_waitcnt lgkmcnt(0)
	v_pk_mul_f32 v[2:3], v[2:3], v[212:213]
	v_pk_mul_f32 v[12:13], v[12:13], v[192:193]
	v_pk_mul_f32 v[8:9], v[8:9], v[196:197]
	v_pk_mul_f32 v[4:5], v[4:5], v[200:201]
	v_pk_mul_f32 v[0:1], v[0:1], v[210:211]
	v_pk_mul_f32 v[30:31], v[30:31], v[194:195]
	v_pk_mul_f32 v[26:27], v[26:27], v[198:199]
	v_pk_mul_f32 v[22:23], v[22:23], v[202:203]
	v_pk_mul_f32 v[18:19], v[18:19], v[212:213]
	v_pk_mul_f32 v[28:29], v[28:29], v[192:193]
	v_pk_mul_f32 v[24:25], v[24:25], v[196:197]
	v_pk_mul_f32 v[20:21], v[20:21], v[200:201]
	v_pk_mul_f32 v[16:17], v[16:17], v[210:211]

; #define SWRITE(b, i) do { *(bf16x8*)(V_lds + (b) * SHM_V + vst0) = sr_[i].vs0; *(bf16x8*)(K_lds + (b) * SHM_K + kst0) = sr_[i].ks0; \
;     if (DQK == 96) *(bf16x8*)(K_lds + (b) * SHM_K + kst1) = sr_[i].ks1; } while (0)
; #define RESC(a) do { if (__any((a) < 1.f)) { if (hi == 0) al_l[r32] = (a); asm volatile("s_waitcnt lgkmcnt(0)" ::: "memory"); \
;     _Pragma("unroll") for (int d = 0; d < 2; ++d) _Pragma("unroll") for (int r = 0; r < 16; ++r) o[d][r] *= al_l[crow(r, hi)]; } } while (0)
; #define BIAS(P0, P1, j) do { if (MODE == 1) { SBAR(); if ((j) >= nA) na_bias(P0, P1, na, rs0 + (j) - nA, hi); SBAR(); } } while (0)
; template <int DQK> __device__ __forceinline__ void partialSM(f32x16& p0, f32x16& p1, float& m_reg, float& mn, float& alpha) {
;   constexpr float SCALE = (DQK == 96) ? 0.10206207261596577f : 0.125f;
;   constexpr float C = SCALE * 1.4426950408889634f;
;   float pmax = p0[0];
; #pragma unroll
;   for (int r = 1; r < 16; ++r) pmax = fmaxf(pmax, p0[r]);
; #pragma unroll
;   for (int r = 0; r < 16; ++r) pmax = fmaxf(pmax, p1[r]);
;   { auto rr = __builtin_amdgcn_permlane32_swap(__float_as_uint(pmax), __float_as_uint(pmax), false, false);
;     pmax = fmaxf(__uint_as_float(rr[0]), __uint_as_float(rr[1])); }
;   if (__builtin_expect(__all(pmax - m_reg <= THR / SCALE), 1)) { mn = m_reg; alpha = 1.f; }
;   else { mn = fmaxf(m_reg, pmax); alpha = __builtin_amdgcn_exp2f((m_reg - mn) * C); m_reg = mn; }
;   float mnC = -mn * C;
; #pragma unroll
;   for (int r = 0; r < 16; ++r) p0[r] = fmaf(p0[r], C, mnC);
; #pragma unroll
;   for (int r = 0; r < 16; ++r) p1[r] = fmaf(p1[r], C, mnC);
; #pragma unroll
;   for (int r = 0; r < 16; ++r) p0[r] = __builtin_amdgcn_exp2f(p0[r]);
; }
; template <int DQK, int MODE, int ldq, int ldk, int ldv> ...
;     ...
;     pv_d0(o, vb0 + (int)SHM_V, pa0, pa1, pa2, pa3); BIAS(pA0, pA1, j + 1); partialSM<DQK>(pA0, pA1, m_reg, mnA, alA);
;     __syncthreads(); SWRITE(1, SO);
;     RESC(alA); __syncthreads();
;   }
.LBB0_306:
	s_waitcnt lgkmcnt(0)
	s_nop 0
	v_mfma_f32_32x32x16_bf16 v[0:15], v[214:217], v[192:195], v[0:15]
	ds_read_b64_tr_b16 v[192:193], v143 offset:0x200
	ds_read_b64_tr_b16 v[194:195], v143 offset:0xa00
	v_max_f32_e32 v112, v48, v49
	v_max3_f32 v112, v112, v50, v51
	v_max3_f32 v112, v112, v52, v53
	v_mfma_f32_32x32x16_bf16 v[0:15], v[218:221], v[196:199], v[0:15]
	ds_read_b64_tr_b16 v[196:197], v143 offset:0x1200
	ds_read_b64_tr_b16 v[198:199], v143 offset:0x1a00
	v_max3_f32 v112, v112, v54, v55
	v_max3_f32 v112, v112, v56, v57
	v_max3_f32 v112, v112, v58, v59
	v_max3_f32 v112, v112, v60, v61
	v_max3_f32 v112, v112, v62, v63
	v_mfma_f32_32x32x16_bf16 v[0:15], v[222:225], v[200:203], v[0:15]
	ds_read_b64_tr_b16 v[200:201], v143 offset:0x2200
	ds_read_b64_tr_b16 v[202:203], v143 offset:0x2a00
	v_max3_f32 v112, v112, v32, v33
	v_max3_f32 v112, v112, v34, v35
	v_max3_f32 v112, v112, v36, v37
	v_max3_f32 v112, v112, v38, v39
	v_max3_f32 v112, v112, v40, v41
	v_mfma_f32_32x32x16_bf16 v[0:15], v[226:229], v[210:213], v[0:15]
	ds_read_b64_tr_b16 v[210:211], v143 offset:0x3200
	ds_read_b64_tr_b16 v[212:213], v143 offset:0x3a00
	v_max3_f32 v112, v112, v42, v43
	v_max3_f32 v112, v112, v44, v45
	v_max3_f32 v112, v112, v46, v47
	v_mov_b32_e32 v113, v112
	s_nop 1
	v_permlane32_swap_b32_e32 v112, v113
	v_max_f32_e32 v112, v112, v113
	v_sub_f32_e32 v113, v112, v158
	v_cmp_ge_f32_e32 vcc, s80, v113
	v_max_f32_e32 v112, v158, v112
	s_waitcnt lgkmcnt(0)
	v_mfma_f32_32x32x16_bf16 v[16:31], v[214:217], v[192:195], v[16:31]
	v_sub_f32_e32 v113, v158, v112
	v_mul_f32_e32 v113, 0x3e16c740, v113
	v_exp_f32_e32 v113, v113
	s_cmp_eq_u64 vcc, exec
	s_cselect_b64 s[0:1], -1, 0
	v_cndmask_b32_e64 v117, v113, 1.0, s[0:1]
	v_cmp_gt_f32_e32 vcc, 1.0, v117
	v_cndmask_b32_e64 v116, v112, v158, s[0:1]
	v_mul_f32_e32 v100, 0xbe16c740, v116
	v_mov_b32_e32 v101, v100
	v_fmamk_f32 v48, v48, 0x3e16c740, v100
	v_fmamk_f32 v49, v49, 0x3e16c740, v100
	v_fmamk_f32 v50, v50, 0x3e16c740, v100
	v_mfma_f32_32x32x16_bf16 v[16:31], v[218:221], v[196:199], v[16:31]
	v_fmamk_f32 v51, v51, 0x3e16c740, v100
	v_fmamk_f32 v52, v52, 0x3e16c740, v100
	v_fmamk_f32 v53, v53, 0x3e16c740, v100
	v_fmamk_f32 v54, v54, 0x3e16c740, v100
	v_fmamk_f32 v55, v55, 0x3e16c740, v100
	v_fmamk_f32 v56, v56, 0x3e16c740, v100
	v_fmamk_f32 v57, v57, 0x3e16c740, v100
	v_fmamk_f32 v58, v58, 0x3e16c740, v100
	v_fmamk_f32 v59, v59, 0x3e16c740, v100
	v_fmamk_f32 v60, v60, 0x3e16c740, v100
	v_mfma_f32_32x32x16_bf16 v[16:31], v[222:225], v[200:203], v[16:31]
	v_fmamk_f32 v61, v61, 0x3e16c740, v100
	v_fmamk_f32 v62, v62, 0x3e16c740, v100
	v_fmac_f32_e32 v101, 0x3e16c740, v63
	v_exp_f32_e32 v126, v48
	v_exp_f32_e32 v160, v49
	v_exp_f32_e32 v127, v50
	v_exp_f32_e32 v161, v51
	v_exp_f32_e32 v158, v52
	v_exp_f32_e32 v162, v53
	v_exp_f32_e32 v159, v54
	v_mfma_f32_32x32x16_bf16 v[16:31], v[226:229], v[210:213], v[16:31]
	v_exp_f32_e32 v163, v55
	v_exp_f32_e32 v118, v56
	v_exp_f32_e32 v121, v57
	v_exp_f32_e32 v119, v58
	v_exp_f32_e32 v122, v59
	v_exp_f32_e32 v120, v60
	v_exp_f32_e32 v123, v61
	v_exp_f32_e32 v124, v62
	v_exp_f32_e32 v125, v101
	v_pk_fma_f32 v[114:115], v[32:33], s[40:41], v[100:101] op_sel_hi:[1,0,0]
	v_add_f32_e32 v32, v155, v156
	v_fmac_f32_e32 v32, v154, v142
	v_add_f32_e32 v142, v164, v165
	v_pk_fma_f32 v[112:113], v[34:35], s[40:41], v[100:101] op_sel_hi:[1,0,0]
	v_pk_fma_f32 v[108:109], v[36:37], s[40:41], v[100:101] op_sel_hi:[1,0,0]
	v_pk_fma_f32 v[104:105], v[38:39], s[40:41], v[100:101] op_sel_hi:[1,0,0]
	v_pk_fma_f32 v[102:103], v[40:41], s[40:41], v[100:101] op_sel_hi:[1,0,0]
	v_pk_fma_f32 v[110:111], v[42:43], s[40:41], v[100:101] op_sel_hi:[1,0,0]
	v_pk_fma_f32 v[106:107], v[44:45], s[40:41], v[100:101] op_sel_hi:[1,0,0]
	v_pk_fma_f32 v[100:101], v[46:47], s[40:41], v[100:101] op_sel_hi:[1,0,0]
	v_fmac_f32_e32 v142, v32, v157
	s_cbranch_vccz .LBB0_310
	s_and_saveexec_b64 s[12:13], s[4:5]
	ds_write_b32 v141, v117 offset:128
	s_or_b64 exec, exec, s[12:13]
	s_waitcnt lgkmcnt(0)
	ds_read_b128 v[192:195], v129 offset:224
	ds_read_b128 v[196:199], v129 offset:192
	ds_read_b128 v[200:203], v129 offset:160
	ds_read_b128 v[210:213], v129 offset:128
	s_waitcnt lgkmcnt(3)
	v_pk_mul_f32 v[14:15], v[14:15], v[194:195]
	s_waitcnt lgkmcnt(2)
	v_pk_mul_f32 v[10:11], v[10:11], v[198:199]
	s_waitcnt lgkmcnt(1)
	v_pk_mul_f32 v[6:7], v[6:7], v[202:203]
	s_waitcnt lgkmcnt(0)
	v_pk_mul_f32 v[2:3], v[2:3], v[212:213]
	v_pk_mul_f32 v[12:13], v[12:13], v[192:193]
	v_pk_mul_f32 v[8:9], v[8:9], v[196:197]
	v_pk_mul_f32 v[4:5], v[4:5], v[200:201]
	v_pk_mul_f32 v[0:1], v[0:1], v[210:211]
	v_pk_mul_f32 v[30:31], v[30:31], v[194:195]
	v_pk_mul_f32 v[26:27], v[26:27], v[198:199]
	v_pk_mul_f32 v[22:23], v[22:23], v[202:203]
	v_pk_mul_f32 v[18:19], v[18:19], v[212:213]
	v_pk_mul_f32 v[28:29], v[28:29], v[192:193]
	v_pk_mul_f32 v[24:25], v[24:25], v[196:197]
	v_pk_mul_f32 v[20:21], v[20:21], v[200:201]
	v_pk_mul_f32 v[16:17], v[16:17], v[210:211]
.LBB0_310:
	s_add_i32 s11, s11, 2
	s_cmpk_gt_u32 s25, 0x80
	s_waitcnt lgkmcnt(0)
	s_barrier
	s_cbranch_scc1 .LBB0_312
	v_mov_b32_e32 v154, v117
	s_branch .LBB0_300
	.p2align 8
; __device__ __forceinline__ void finishSM(f32x16& p0, f32x16& p1, float alpha, float& l_reg, bf16x8& pa0, bf16x8& pa1, bf16x8& pa2, bf16x8& pa3) {
; #pragma unroll
;   for (int r = 0; r < 16; ++r) p1[r] = __builtin_amdgcn_exp2f(p1[r]);
;   float ps = 0;
; #pragma unroll
;   for (int r = 0; r < 16; ++r) ps += p0[r];
; #pragma unroll
;   for (int r = 0; r < 16; ++r) ps += p1[r];
;   { auto rr = __builtin_amdgcn_permlane32_swap(__float_as_uint(ps), __float_as_uint(ps), false, false);
;     ps = __uint_as_float(rr[0]) + __uint_as_float(rr[1]); }
;   l_reg = l_reg * alpha + ps;
;     ...
;   PK4(p0, 0, pa0); PK4(p0, 8, pa1); PK4(p1, 0, pa2); PK4(p1, 8, pa3);
;     ...
; }
; template <int DQK> __device__ __forceinline__ void qkt(f32x16& p0, f32x16& p1, const char* Ks, const bf16x8* qr, int r32, int hi) {
;   p0 = f32x16{}; p1 = f32x16{};
; #pragma unroll
;   for (int d0 = 0; d0 < DQK / 16; ++d0) { int cb = (d0 * 16 + hi * 8) * 2;
;     bf16x8 b0 = *reinterpret_cast<const bf16x8*>(Ks + KSWZ(r32, cb));
;     bf16x8 b1 = *reinterpret_cast<const bf16x8*>(Ks + KSWZ(32 + r32, cb));
;     p0 = __builtin_amdgcn_mfma_f32_32x32x16_bf16(b0, qr[d0], p0, 0, 0, 0);
;     p1 = __builtin_amdgcn_mfma_f32_32x32x16_bf16(b1, qr[d0], p1, 0, 0, 0); }
; }
.Lmy_h1B:
	s_waitcnt vmcnt(0)
	ds_write_b128 v146, v[88:91] offset:32768
	ds_write_b128 v145, v[92:95] offset:16384
	v_exp_f32_e32 v117, v114
	v_exp_f32_e32 v157, v115
	v_exp_f32_e32 v108, v108
	v_exp_f32_e32 v109, v109
	v_exp_f32_e32 v104, v104
	v_exp_f32_e32 v105, v105
	v_exp_f32_e32 v102, v102
	v_exp_f32_e32 v103, v103
	v_exp_f32_e32 v110, v110
	v_exp_f32_e32 v111, v111
	v_exp_f32_e32 v106, v106
	v_exp_f32_e32 v107, v107
	v_exp_f32_e32 v100, v100
	v_exp_f32_e32 v101, v101
	v_exp_f32_e32 v164, v112
	v_add_f32_e32 v112, 0, v126
	v_add_f32_e32 v112, v160, v112
	v_add_f32_e32 v112, v127, v112
	v_add_f32_e32 v112, v161, v112
	v_add_f32_e32 v112, v158, v112
	v_add_f32_e32 v112, v162, v112
	v_add_f32_e32 v112, v159, v112
	v_add_f32_e32 v112, v163, v112
	v_add_f32_e32 v112, v118, v112
	v_add_f32_e32 v112, v121, v112
	v_add_f32_e32 v112, v119, v112
	v_add_f32_e32 v112, v122, v112
	v_add_f32_e32 v112, v120, v112
	v_add_f32_e32 v112, v123, v112
	v_add_f32_e32 v112, v124, v112
	v_exp_f32_e32 v165, v113
	v_add_f32_e32 v112, v125, v112
	v_add_f32_e32 v112, v117, v112
	v_add_f32_e32 v112, v157, v112
	v_add_f32_e32 v112, v164, v112
	v_add_f32_e32 v112, v165, v112
	v_add_f32_e32 v112, v108, v112
	v_add_f32_e32 v112, v109, v112
	v_add_f32_e32 v112, v104, v112
	v_add_f32_e32 v112, v105, v112
	v_add_f32_e32 v112, v102, v112
	v_add_f32_e32 v112, v103, v112
	v_add_f32_e32 v112, v110, v112
	v_add_f32_e32 v112, v111, v112
	v_add_f32_e32 v112, v106, v112
	v_add_f32_e32 v112, v107, v112
	v_add_f32_e32 v112, v100, v112
	v_add_f32_e32 v155, v101, v112
	v_mov_b32_e32 v156, v155
	v_cvt_pk_bf16_f32 v214, v126, v160
	v_cvt_pk_bf16_f32 v215, v127, v161
	v_cvt_pk_bf16_f32 v216, v158, v162
	s_nop 1
	v_permlane32_swap_b32_e32 v155, v156
	v_cvt_pk_bf16_f32 v217, v159, v163
	v_permlane32_swap_b32_e32 v214, v216
	v_cvt_pk_bf16_f32 v218, v118, v121
	v_cvt_pk_bf16_f32 v219, v119, v122
	v_cvt_pk_bf16_f32 v220, v120, v123
	v_cvt_pk_bf16_f32 v221, v124, v125
	v_cvt_pk_bf16_f32 v222, v117, v157
	v_cvt_pk_bf16_f32 v223, v164, v165
	v_cvt_pk_bf16_f32 v224, v108, v109
	v_cvt_pk_bf16_f32 v225, v104, v105
	v_cvt_pk_bf16_f32 v226, v102, v103
	v_cvt_pk_bf16_f32 v227, v110, v111
	v_cvt_pk_bf16_f32 v228, v106, v107
	v_cvt_pk_bf16_f32 v229, v100, v101
	v_permlane32_swap_b32_e32 v215, v217
	v_permlane32_swap_b32_e32 v218, v220
	v_permlane32_swap_b32_e32 v219, v221
	v_permlane32_swap_b32_e32 v222, v224
	v_permlane32_swap_b32_e32 v223, v225
	v_permlane32_swap_b32_e32 v226, v228
	v_permlane32_swap_b32_e32 v227, v229
	s_cmpk_lt_u32 s25, 0x7e
	s_cselect_b32 s0, 0, 0xffffff80
	s_cselect_b32 s1, s10, s24
	s_add_i32 s0, s0, s11
	s_lshl_b32 s0, s0, 6
	s_add_i32 s0, s0, s1
	s_sub_i32 s0, s0, 64
	s_ashr_i32 s1, s0, 31
	s_cmpk_lt_u32 s25, 0x7f
	s_cselect_b32 s98, 0, 0xffffff80
	s_cselect_b32 s99, s10, s24
	s_add_i32 s98, s98, s11
	s_lshl_b32 s98, s98, 6
	s_add_i32 s98, s98, s99
	s_addk_i32 s98, 0xff80
	s_ashr_i32 s99, s98, 31
	v_lshl_add_u64 v[100:101], s[0:1], 0, v[130:131]
	v_lshl_add_u64 v[104:105], s[98:99], 0, v[130:131]
	v_lshlrev_b64 v[104:105], 9, v[104:105]
	v_lshl_add_u64 v[104:105], v[134:135], 0, v[104:105]
	v_mad_u64_u32 v[102:103], s[12:13], v100, s70, v[136:137]
	v_mad_i32_i24 v103, v101, s70, v103
	global_load_dwordx4 v[184:187], v[102:103], off
	s_nop 0
	global_load_dwordx4 v[188:191], v[104:105], off
	s_nop 0
	ds_read_b64_tr_b16 v[192:193], v144 offset:0
	ds_read_b64_tr_b16 v[194:195], v144 offset:0x800
	ds_read_b64_tr_b16 v[196:197], v144 offset:0x1000
	ds_read_b64_tr_b16 v[198:199], v144 offset:0x1800
	ds_read_b64_tr_b16 v[200:201], v144 offset:0x2000
	ds_read_b64_tr_b16 v[202:203], v144 offset:0x2800
	ds_read_b64_tr_b16 v[210:211], v144 offset:0x3000
	ds_read_b64_tr_b16 v[212:213], v144 offset:0x3800
	s_waitcnt lgkmcnt(0)
	s_nop 0
	v_mfma_f32_32x32x16_bf16 v[0:15], v[214:217], v[192:195], v[0:15]
	ds_read_b64_tr_b16 v[192:193], v144 offset:0x200
	ds_read_b64_tr_b16 v[194:195], v144 offset:0xa00
	v_mfma_f32_32x32x16_bf16 v[0:15], v[218:221], v[196:199], v[0:15]
	ds_read_b64_tr_b16 v[196:197], v144 offset:0x1200
	ds_read_b64_tr_b16 v[198:199], v144 offset:0x1a00
	v_mfma_f32_32x32x16_bf16 v[0:15], v[222:225], v[200:203], v[0:15]
	ds_read_b64_tr_b16 v[200:201], v144 offset:0x2200
	ds_read_b64_tr_b16 v[202:203], v144 offset:0x2a00
	v_mfma_f32_32x32x16_bf16 v[0:15], v[226:229], v[210:213], v[0:15]
	ds_read_b64_tr_b16 v[210:211], v144 offset:0x3200
	ds_read_b64_tr_b16 v[212:213], v144 offset:0x3a00
	s_waitcnt lgkmcnt(0)
	v_mfma_f32_32x32x16_bf16 v[16:31], v[214:217], v[192:195], v[16:31]
	v_mfma_f32_32x32x16_bf16 v[16:31], v[218:221], v[196:199], v[16:31]
	v_mfma_f32_32x32x16_bf16 v[16:31], v[222:225], v[200:203], v[16:31]
	v_mfma_f32_32x32x16_bf16 v[16:31], v[226:229], v[210:213], v[16:31]
	ds_read_b128 v[32:35], v148 offset:49152
	ds_read_b128 v[36:39], v148 offset:57344
	ds_read_b128 v[164:167], v152 offset:49152
	ds_read_b128 v[168:171], v152 offset:57344
	s_waitcnt lgkmcnt(3)
	v_mfma_f32_32x32x16_bf16 v[48:63], v[32:35], v[84:87], 0
	s_waitcnt lgkmcnt(2)
	v_mfma_f32_32x32x16_bf16 v[32:47], v[36:39], v[84:87], 0
	s_waitcnt lgkmcnt(1)
	v_mfma_f32_32x32x16_bf16 v[48:63], v[164:167], v[80:83], v[48:63]
	s_waitcnt lgkmcnt(0)
	v_mfma_f32_32x32x16_bf16 v[32:47], v[168:171], v[80:83], v[32:47]
	ds_read_b128 v[164:167], v151 offset:49152
	ds_read_b128 v[168:171], v151 offset:57344
	s_waitcnt lgkmcnt(1)
	v_mfma_f32_32x32x16_bf16 v[48:63], v[164:167], v[76:79], v[48:63]
	s_waitcnt lgkmcnt(0)
	v_mfma_f32_32x32x16_bf16 v[32:47], v[168:171], v[76:79], v[32:47]
	ds_read_b128 v[164:167], v149 offset:49152
	ds_read_b128 v[168:171], v149 offset:57344
	s_waitcnt lgkmcnt(1)
; template <int DQK> __device__ __forceinline__ void partialSM(f32x16& p0, f32x16& p1, float& m_reg, float& mn, float& alpha) {
;   constexpr float SCALE = (DQK == 96) ? 0.10206207261596577f : 0.125f;
;   constexpr float C = SCALE * 1.4426950408889634f;
;   float pmax = p0[0];
; #pragma unroll
;   for (int r = 1; r < 16; ++r) pmax = fmaxf(pmax, p0[r]);
; #pragma unroll
;   for (int r = 0; r < 16; ++r) pmax = fmaxf(pmax, p1[r]);
;   { auto rr = __builtin_amdgcn_permlane32_swap(__float_as_uint(pmax), __float_as_uint(pmax), false, false);
;     pmax = fmaxf(__uint_as_float(rr[0]), __uint_as_float(rr[1])); }
;   if (__builtin_expect(__all(pmax - m_reg <= THR / SCALE), 1)) { mn = m_reg; alpha = 1.f; }
;   else { mn = fmaxf(m_reg, pmax); alpha = __builtin_amdgcn_exp2f((m_reg - mn) * C); m_reg = mn; }
;   float mnC = -mn * C;
; #pragma unroll
;   for (int r = 0; r < 16; ++r) p0[r] = fmaf(p0[r], C, mnC);
; #pragma unroll
;   for (int r = 0; r < 16; ++r) p1[r] = fmaf(p1[r], C, mnC);
; #pragma unroll
;   for (int r = 0; r < 16; ++r) p0[r] = __builtin_amdgcn_exp2f(p0[r]);
; }
	v_mfma_f32_32x32x16_bf16 v[48:63], v[164:167], v[72:75], v[48:63]
	s_waitcnt lgkmcnt(0)
	v_mfma_f32_32x32x16_bf16 v[32:47], v[168:171], v[72:75], v[32:47]
	ds_read_b128 v[164:167], v150 offset:49152
	ds_read_b128 v[168:171], v150 offset:57344
	s_waitcnt lgkmcnt(1)
	v_mfma_f32_32x32x16_bf16 v[48:63], v[164:167], v[68:71], v[48:63]
	s_waitcnt lgkmcnt(0)
	v_mfma_f32_32x32x16_bf16 v[32:47], v[168:171], v[68:71], v[32:47]
	ds_read_b128 v[164:167], v153 offset:49152
	ds_read_b128 v[168:171], v153 offset:57344
	s_waitcnt lgkmcnt(1)
	v_mfma_f32_32x32x16_bf16 v[48:63], v[164:167], v[64:67], v[48:63]
	s_waitcnt lgkmcnt(0)
	v_mfma_f32_32x32x16_bf16 v[32:47], v[168:171], v[64:67], v[32:47]
	s_nop 7
	s_nop 4
	v_max_f32_e32 v112, v48, v49
	v_max3_f32 v112, v112, v50, v51
	v_max3_f32 v112, v112, v52, v53
	v_max3_f32 v112, v112, v54, v55
	v_max3_f32 v112, v112, v56, v57
	v_max3_f32 v112, v112, v58, v59
	v_max3_f32 v112, v112, v60, v61
	v_max3_f32 v112, v112, v62, v63
	v_max3_f32 v112, v112, v32, v33
	v_max3_f32 v112, v112, v34, v35
	v_max3_f32 v112, v112, v36, v37
	v_max3_f32 v112, v112, v38, v39
	v_max3_f32 v112, v112, v40, v41
	v_max3_f32 v112, v112, v42, v43
	v_max3_f32 v112, v112, v44, v45
	v_max3_f32 v112, v112, v46, v47
	v_mov_b32_e32 v113, v112
	s_nop 1
	v_permlane32_swap_b32_e32 v112, v113
	v_max_f32_e32 v112, v112, v113
	v_sub_f32_e32 v113, v112, v116
	v_cmp_ge_f32_e32 vcc, s80, v113
	v_max_f32_e32 v112, v116, v112
	v_sub_f32_e32 v113, v116, v112
	v_mul_f32_e32 v113, 0x3e16c740, v113
	v_exp_f32_e32 v113, v113
	s_cmp_eq_u64 vcc, exec
	s_cselect_b64 s[0:1], -1, 0
	v_cndmask_b32_e64 v157, v113, 1.0, s[0:1]
	v_cmp_gt_f32_e32 vcc, 1.0, v157
	v_cndmask_b32_e64 v158, v112, v116, s[0:1]
	v_mul_f32_e32 v159, 0xbe16c740, v158
	v_fmamk_f32 v48, v48, 0x3e16c740, v159
	v_fmamk_f32 v49, v49, 0x3e16c740, v159
	v_fmamk_f32 v50, v50, 0x3e16c740, v159
	v_fmamk_f32 v51, v51, 0x3e16c740, v159
	v_fmamk_f32 v52, v52, 0x3e16c740, v159
	v_fmamk_f32 v53, v53, 0x3e16c740, v159
	v_fmamk_f32 v54, v54, 0x3e16c740, v159
	v_fmamk_f32 v55, v55, 0x3e16c740, v159
	v_fmamk_f32 v56, v56, 0x3e16c740, v159
	v_fmamk_f32 v57, v57, 0x3e16c740, v159
	v_fmamk_f32 v58, v58, 0x3e16c740, v159
	v_fmamk_f32 v59, v59, 0x3e16c740, v159
	v_fmamk_f32 v60, v60, 0x3e16c740, v159
	v_fmamk_f32 v61, v61, 0x3e16c740, v159
	v_fmamk_f32 v62, v62, 0x3e16c740, v159
	v_fmamk_f32 v63, v63, 0x3e16c740, v159
	v_exp_f32_e32 v112, v48
	v_exp_f32_e32 v127, v49
	v_exp_f32_e32 v113, v50
	v_exp_f32_e32 v126, v51
	v_exp_f32_e32 v114, v52
	v_exp_f32_e32 v125, v53
	v_exp_f32_e32 v115, v54
	v_exp_f32_e32 v124, v55
	v_exp_f32_e32 v116, v56
	v_exp_f32_e32 v123, v57
	v_exp_f32_e32 v117, v58
	v_exp_f32_e32 v122, v59
	v_exp_f32_e32 v118, v60
	v_exp_f32_e32 v121, v61
	v_exp_f32_e32 v119, v62
	v_exp_f32_e32 v120, v63
	v_fmamk_f32 v164, v42, 0x3e16c740, v159
	v_fmamk_f32 v165, v43, 0x3e16c740, v159
	v_fmamk_f32 v167, v32, 0x3e16c740, v159
	v_fmamk_f32 v168, v33, 0x3e16c740, v159
	v_fmamk_f32 v169, v34, 0x3e16c740, v159
	v_fmamk_f32 v170, v35, 0x3e16c740, v159
	v_fmamk_f32 v171, v36, 0x3e16c740, v159
	v_fmamk_f32 v172, v37, 0x3e16c740, v159
	v_fmamk_f32 v160, v38, 0x3e16c740, v159
	v_fmamk_f32 v161, v39, 0x3e16c740, v159
	v_fmamk_f32 v162, v40, 0x3e16c740, v159
	v_fmamk_f32 v163, v41, 0x3e16c740, v159
	v_fmamk_f32 v166, v44, 0x3e16c740, v159
	v_fmamk_f32 v173, v45, 0x3e16c740, v159
	v_fmamk_f32 v174, v46, 0x3e16c740, v159
	v_fmac_f32_e32 v159, 0x3e16c740, v47
	s_cbranch_vccz .Lmy_h1B_304
	s_and_saveexec_b64 s[12:13], s[4:5]
	ds_write_b32 v141, v157 offset:128
	s_or_b64 exec, exec, s[12:13]
	s_waitcnt lgkmcnt(0)
	ds_read_b128 v[192:195], v129 offset:224
	ds_read_b128 v[196:199], v129 offset:192
	ds_read_b128 v[200:203], v129 offset:160
	ds_read_b128 v[210:213], v129 offset:128
	s_waitcnt lgkmcnt(3)
	v_pk_mul_f32 v[14:15], v[14:15], v[194:195]
	s_waitcnt lgkmcnt(2)
	v_pk_mul_f32 v[10:11], v[10:11], v[198:199]
	s_waitcnt lgkmcnt(1)
	v_pk_mul_f32 v[6:7], v[6:7], v[202:203]
	s_waitcnt lgkmcnt(0)
	v_pk_mul_f32 v[2:3], v[2:3], v[212:213]
	v_pk_mul_f32 v[12:13], v[12:13], v[192:193]
	v_pk_mul_f32 v[8:9], v[8:9], v[196:197]
	v_pk_mul_f32 v[4:5], v[4:5], v[200:201]
	v_pk_mul_f32 v[0:1], v[0:1], v[210:211]
	v_pk_mul_f32 v[30:31], v[30:31], v[194:195]
	v_pk_mul_f32 v[26:27], v[26:27], v[198:199]
	v_pk_mul_f32 v[22:23], v[22:23], v[202:203]
	v_pk_mul_f32 v[18:19], v[18:19], v[212:213]
	v_pk_mul_f32 v[28:29], v[28:29], v[192:193]
	v_pk_mul_f32 v[24:25], v[24:25], v[196:197]
	v_pk_mul_f32 v[20:21], v[20:21], v[200:201]
	v_pk_mul_f32 v[16:17], v[16:17], v[210:211]
; __device__ __forceinline__ void finishSM(f32x16& p0, f32x16& p1, float alpha, float& l_reg, bf16x8& pa0, bf16x8& pa1, bf16x8& pa2, bf16x8& pa3) {
; #pragma unroll
;   for (int r = 0; r < 16; ++r) p1[r] = __builtin_amdgcn_exp2f(p1[r]);
;   float ps = 0;
; #pragma unroll
;   for (int r = 0; r < 16; ++r) ps += p0[r];
; #pragma unroll
;   for (int r = 0; r < 16; ++r) ps += p1[r];
;   { auto rr = __builtin_amdgcn_permlane32_swap(__float_as_uint(ps), __float_as_uint(ps), false, false);
;     ps = __uint_as_float(rr[0]) + __uint_as_float(rr[1]); }
;   l_reg = l_reg * alpha + ps;
;     ...
;   PK4(p0, 0, pa0); PK4(p0, 8, pa1); PK4(p1, 0, pa2); PK4(p1, 8, pa3);
;     ...
; }
.Lmy_h1B_304:
	s_waitcnt lgkmcnt(0)
	s_barrier
	s_waitcnt vmcnt(0)
	ds_write_b128 v146, v[184:187] offset:49152
	ds_write_b128 v145, v[188:191]
	v_exp_f32_e32 v175, v164
	v_add_f32_e32 v164, 0, v112
	v_add_f32_e32 v164, v127, v164
	v_add_f32_e32 v164, v113, v164
	v_add_f32_e32 v164, v126, v164
	v_add_f32_e32 v164, v114, v164
	v_add_f32_e32 v164, v125, v164
	v_add_f32_e32 v164, v115, v164
	v_add_f32_e32 v164, v124, v164
	v_add_f32_e32 v164, v116, v164
	v_add_f32_e32 v164, v123, v164
	v_add_f32_e32 v164, v117, v164
	v_add_f32_e32 v164, v122, v164
	v_exp_f32_e32 v167, v167
	v_add_f32_e32 v164, v118, v164
	v_exp_f32_e32 v168, v168
	v_add_f32_e32 v164, v121, v164
	v_exp_f32_e32 v169, v169
	v_add_f32_e32 v164, v119, v164
	v_exp_f32_e32 v170, v170
	v_add_f32_e32 v164, v120, v164
	v_exp_f32_e32 v171, v171
	v_add_f32_e32 v164, v167, v164
	v_exp_f32_e32 v172, v172
	v_add_f32_e32 v164, v168, v164
	v_exp_f32_e32 v160, v160
	v_add_f32_e32 v164, v169, v164
	v_exp_f32_e32 v161, v161
	v_add_f32_e32 v164, v170, v164
	v_exp_f32_e32 v162, v162
	v_add_f32_e32 v164, v171, v164
	v_exp_f32_e32 v163, v163
	v_add_f32_e32 v164, v172, v164
	v_add_f32_e32 v164, v160, v164
	v_add_f32_e32 v164, v161, v164
	v_exp_f32_e32 v166, v166
	v_add_f32_e32 v164, v162, v164
	v_exp_f32_e32 v173, v173
	v_add_f32_e32 v164, v163, v164
	v_exp_f32_e32 v174, v174
	v_add_f32_e32 v164, v175, v164
	v_exp_f32_e32 v159, v159
	v_cvt_pk_bf16_f32 v214, v112, v127
	v_cvt_pk_bf16_f32 v215, v113, v126
	v_cvt_pk_bf16_f32 v216, v114, v125
	v_cvt_pk_bf16_f32 v217, v115, v124
	v_cvt_pk_bf16_f32 v218, v116, v123
	v_cvt_pk_bf16_f32 v219, v117, v122
	v_exp_f32_e32 v176, v165
	v_cvt_pk_bf16_f32 v220, v118, v121
	v_cvt_pk_bf16_f32 v221, v119, v120
	v_cvt_pk_bf16_f32 v222, v167, v168
	v_cvt_pk_bf16_f32 v223, v169, v170
	v_cvt_pk_bf16_f32 v224, v171, v172
	s_nop 0
	v_add_f32_e32 v164, v176, v164
	v_add_f32_e32 v164, v166, v164
	v_add_f32_e32 v164, v173, v164
	v_add_f32_e32 v164, v174, v164
	v_add_f32_e32 v164, v159, v164
	v_mov_b32_e32 v165, v164
	v_cvt_pk_bf16_f32 v225, v160, v161
	v_cvt_pk_bf16_f32 v226, v162, v163
	v_cvt_pk_bf16_f32 v227, v175, v176
	v_cvt_pk_bf16_f32 v228, v166, v173
	v_cvt_pk_bf16_f32 v229, v174, v159
	s_nop 1
	v_permlane32_swap_b32_e32 v164, v165
	v_permlane32_swap_b32_e32 v214, v216
	v_permlane32_swap_b32_e32 v215, v217
	v_permlane32_swap_b32_e32 v218, v220
	v_permlane32_swap_b32_e32 v219, v221
	v_permlane32_swap_b32_e32 v222, v224
	v_permlane32_swap_b32_e32 v223, v225
	v_permlane32_swap_b32_e32 v226, v228
	v_permlane32_swap_b32_e32 v227, v229
	s_cmpk_lt_u32 s25, 0x7e
	s_cselect_b32 s98, 0, 0xffffff80
	s_cselect_b32 s99, s10, s24
	s_add_i32 s98, s98, s11
	s_lshl_b32 s98, s98, 6
	s_add_i32 s98, s98, s99
	s_sub_i32 s98, s98, 64
	s_ashr_i32 s99, s98, 31
	v_lshl_add_u64 v[92:93], s[98:99], 0, v[130:131]
	v_lshlrev_b64 v[92:93], 9, v[92:93]
	v_lshl_add_u64 v[92:93], v[134:135], 0, v[92:93]
	global_load_dwordx4 v[92:95], v[92:93], off
	s_cmpk_gt_u32 s25, 0x80
	s_cbranch_scc1 .Lmy_h2B_306
	s_cmpk_lt_u32 s25, 0x7d
	s_cselect_b32 s0, 0, 0xffffff80
	s_cselect_b32 s1, s10, s24
	s_add_i32 s0, s0, s11
	s_lshl_b32 s0, s0, 6
	s_add_i32 s0, s0, s1
	s_ashr_i32 s1, s0, 31
	v_lshl_add_u64 v[88:89], s[0:1], 0, v[130:131]
	v_mad_u64_u32 v[90:91], s[12:13], v88, s70, v[136:137]
	v_mad_i32_i24 v91, v89, s70, v91
	global_load_dwordx4 v[88:91], v[90:91], off
	s_nop 0
	s_nop 0
; template <int DQK> __device__ __forceinline__ void partialSM(f32x16& p0, f32x16& p1, float& m_reg, float& mn, float& alpha) {
;   constexpr float SCALE = (DQK == 96) ? 0.10206207261596577f : 0.125f;
; template <int DQK> __device__ __forceinline__ void qkt(f32x16& p0, f32x16& p1, const char* Ks, const bf16x8* qr, int r32, int hi) {
;   p0 = f32x16{}; p1 = f32x16{};
; #pragma unroll
;   for (int d0 = 0; d0 < DQK / 16; ++d0) { int cb = (d0 * 16 + hi * 8) * 2;
;     bf16x8 b0 = *reinterpret_cast<const bf16x8*>(Ks + KSWZ(r32, cb));
;     bf16x8 b1 = *reinterpret_cast<const bf16x8*>(Ks + KSWZ(32 + r32, cb));
;     p0 = __builtin_amdgcn_mfma_f32_32x32x16_bf16(b0, qr[d0], p0, 0, 0, 0);
;     p1 = __builtin_amdgcn_mfma_f32_32x32x16_bf16(b1, qr[d0], p1, 0, 0, 0); }
; }
; __device__ __forceinline__ int v_st(int k, int c) { const int kk = (k & ~0xC) | ((k & 4) << 1) | ((k & 8) >> 1); return ((kk >> 3) * 4 + (c >> 5)) * 512 + ((kk & 7) * 32 + (c & 31)) * 2; }
; __device__ __forceinline__ int v_rd_base(int lane) { return ((lane & 3) << 3) | (((lane >> 2) & 3) << 6) | (((lane >> 4) & 1) << 5) | (((lane >> 5) & 1) << 8); }
; template <int OFF> __device__ __forceinline__ s16x4 tr_read(int vb) {
;   s16x4 r; asm volatile("ds_read_b64_tr_b16 %0, %1 offset:%2" : "=&v"(r) : "v"(vb), "i"(OFF) : "memory"); return r;
; }
; template <int D0> __device__ __forceinline__ void pv_one(f32x16& od, int vb, bf16x8 pa0, bf16x8 pa1, bf16x8 pa2, bf16x8 pa3) {
;   const s16x4 l0 = tr_read<v_rd_off(D0, 0, 0)>(vb), h0 = tr_read<v_rd_off(D0, 0, 1)>(vb), l1 = tr_read<v_rd_off(D0, 1, 0)>(vb), h1 = tr_read<v_rd_off(D0, 1, 1)>(vb);
;   const s16x4 l2 = tr_read<v_rd_off(D0, 2, 0)>(vb), h2 = tr_read<v_rd_off(D0, 2, 1)>(vb), l3 = tr_read<v_rd_off(D0, 3, 0)>(vb), h3 = tr_read<v_rd_off(D0, 3, 1)>(vb);
;   asm volatile("s_waitcnt lgkmcnt(0)" ::: "memory"); SBAR();
;   od = __builtin_amdgcn_mfma_f32_32x32x16_bf16(pa0, PKLH(l0, h0), od, 0, 0, 0);
;   od = __builtin_amdgcn_mfma_f32_32x32x16_bf16(pa1, PKLH(l1, h1), od, 0, 0, 0);
;   od = __builtin_amdgcn_mfma_f32_32x32x16_bf16(pa2, PKLH(l2, h2), od, 0, 0, 0);
;   od = __builtin_amdgcn_mfma_f32_32x32x16_bf16(pa3, PKLH(l3, h3), od, 0, 0, 0);
; }
; __device__ __forceinline__ void pv_d0(f32x16* o, int vb, bf16x8 pa0, bf16x8 pa1, bf16x8 pa2, bf16x8 pa3) {
;   pv_one<0>(o[0], vb, pa0, pa1, pa2, pa3); pv_one<1>(o[1], vb, pa0, pa1, pa2, pa3);
; }
.Lmy_h2B_306:
	ds_read_b64_tr_b16 v[192:193], v143 offset:0
	ds_read_b64_tr_b16 v[194:195], v143 offset:0x800
	ds_read_b64_tr_b16 v[196:197], v143 offset:0x1000
	ds_read_b64_tr_b16 v[198:199], v143 offset:0x1800
	ds_read_b64_tr_b16 v[200:201], v143 offset:0x2000
	ds_read_b64_tr_b16 v[202:203], v143 offset:0x2800
	ds_read_b64_tr_b16 v[210:211], v143 offset:0x3000
	ds_read_b64_tr_b16 v[212:213], v143 offset:0x3800
	s_waitcnt lgkmcnt(0)
	s_nop 0
	v_mfma_f32_32x32x16_bf16 v[0:15], v[214:217], v[192:195], v[0:15]
	ds_read_b64_tr_b16 v[192:193], v143 offset:0x200
	ds_read_b64_tr_b16 v[194:195], v143 offset:0xa00
	v_mfma_f32_32x32x16_bf16 v[0:15], v[218:221], v[196:199], v[0:15]
	ds_read_b64_tr_b16 v[196:197], v143 offset:0x1200
	ds_read_b64_tr_b16 v[198:199], v143 offset:0x1a00
	v_mfma_f32_32x32x16_bf16 v[0:15], v[222:225], v[200:203], v[0:15]
	ds_read_b64_tr_b16 v[200:201], v143 offset:0x2200
	ds_read_b64_tr_b16 v[202:203], v143 offset:0x2a00
	v_mfma_f32_32x32x16_bf16 v[0:15], v[226:229], v[210:213], v[0:15]
	ds_read_b64_tr_b16 v[210:211], v143 offset:0x3200
	ds_read_b64_tr_b16 v[212:213], v143 offset:0x3a00
	s_waitcnt lgkmcnt(0)
	v_mfma_f32_32x32x16_bf16 v[16:31], v[214:217], v[192:195], v[16:31]
	v_mfma_f32_32x32x16_bf16 v[16:31], v[218:221], v[196:199], v[16:31]
	v_mfma_f32_32x32x16_bf16 v[16:31], v[222:225], v[200:203], v[16:31]
	v_mfma_f32_32x32x16_bf16 v[16:31], v[226:229], v[210:213], v[16:31]
	ds_read_b128 v[32:35], v148 offset:32768
	ds_read_b128 v[36:39], v148 offset:40960
	ds_read_b128 v[176:179], v152 offset:32768
	ds_read_b128 v[180:183], v152 offset:40960
	s_waitcnt lgkmcnt(3)
	v_mfma_f32_32x32x16_bf16 v[48:63], v[32:35], v[84:87], 0
	s_waitcnt lgkmcnt(2)
	v_mfma_f32_32x32x16_bf16 v[32:47], v[36:39], v[84:87], 0
	s_waitcnt lgkmcnt(1)
	v_mfma_f32_32x32x16_bf16 v[48:63], v[176:179], v[80:83], v[48:63]
	s_waitcnt lgkmcnt(0)
	v_mfma_f32_32x32x16_bf16 v[32:47], v[180:183], v[80:83], v[32:47]
	ds_read_b128 v[176:179], v151 offset:32768
	ds_read_b128 v[180:183], v151 offset:40960
	s_waitcnt lgkmcnt(1)
	v_mfma_f32_32x32x16_bf16 v[48:63], v[176:179], v[76:79], v[48:63]
	s_waitcnt lgkmcnt(0)
	v_mfma_f32_32x32x16_bf16 v[32:47], v[180:183], v[76:79], v[32:47]
	ds_read_b128 v[176:179], v149 offset:32768
	ds_read_b128 v[180:183], v149 offset:40960
	s_waitcnt lgkmcnt(1)
	v_mfma_f32_32x32x16_bf16 v[48:63], v[176:179], v[72:75], v[48:63]
	s_waitcnt lgkmcnt(0)
	v_mfma_f32_32x32x16_bf16 v[32:47], v[180:183], v[72:75], v[32:47]
	ds_read_b128 v[176:179], v150 offset:32768
	ds_read_b128 v[180:183], v150 offset:40960
	s_waitcnt lgkmcnt(1)
	v_mfma_f32_32x32x16_bf16 v[48:63], v[176:179], v[68:71], v[48:63]
	s_waitcnt lgkmcnt(0)
	v_mfma_f32_32x32x16_bf16 v[32:47], v[180:183], v[68:71], v[32:47]
	ds_read_b128 v[176:179], v153 offset:32768
	ds_read_b128 v[180:183], v153 offset:40960
	s_waitcnt lgkmcnt(1)
	v_mfma_f32_32x32x16_bf16 v[48:63], v[176:179], v[64:67], v[48:63]
	s_waitcnt lgkmcnt(0)
	v_mfma_f32_32x32x16_bf16 v[32:47], v[180:183], v[64:67], v[32:47]
	s_nop 7
	s_nop 4
	v_max_f32_e32 v112, v48, v49
	v_max3_f32 v112, v112, v50, v51
	v_max3_f32 v112, v112, v52, v53
	v_max3_f32 v112, v112, v54, v55
	v_max3_f32 v112, v112, v56, v57
	v_max3_f32 v112, v112, v58, v59
	v_max3_f32 v112, v112, v60, v61
	v_max3_f32 v112, v112, v62, v63
	v_max3_f32 v112, v112, v32, v33
	v_max3_f32 v112, v112, v34, v35
	v_max3_f32 v112, v112, v36, v37
	v_max3_f32 v112, v112, v38, v39
	v_max3_f32 v112, v112, v40, v41
	v_max3_f32 v112, v112, v42, v43
	v_max3_f32 v112, v112, v44, v45
	v_max3_f32 v112, v112, v46, v47
	v_mov_b32_e32 v113, v112
	s_nop 1
	v_permlane32_swap_b32_e32 v112, v113
	v_max_f32_e32 v112, v112, v113
	v_sub_f32_e32 v113, v112, v158
	v_cmp_ge_f32_e32 vcc, s80, v113
	v_max_f32_e32 v112, v158, v112
	v_sub_f32_e32 v113, v158, v112
	v_mul_f32_e32 v113, 0x3e16c740, v113
	v_exp_f32_e32 v113, v113
	s_cmp_eq_u64 vcc, exec
	s_cselect_b64 s[0:1], -1, 0
	v_cndmask_b32_e64 v117, v113, 1.0, s[0:1]
	v_cmp_gt_f32_e32 vcc, 1.0, v117
	v_cndmask_b32_e64 v116, v112, v158, s[0:1]
	v_mul_f32_e32 v100, 0xbe16c740, v116
	v_mov_b32_e32 v101, v100
	v_fmamk_f32 v48, v48, 0x3e16c740, v100
	v_fmamk_f32 v49, v49, 0x3e16c740, v100
	v_fmamk_f32 v50, v50, 0x3e16c740, v100
	v_fmamk_f32 v51, v51, 0x3e16c740, v100
	v_fmamk_f32 v52, v52, 0x3e16c740, v100
	v_fmamk_f32 v53, v53, 0x3e16c740, v100
	v_fmamk_f32 v54, v54, 0x3e16c740, v100
	v_fmamk_f32 v55, v55, 0x3e16c740, v100
	v_fmamk_f32 v56, v56, 0x3e16c740, v100
	v_fmamk_f32 v57, v57, 0x3e16c740, v100
	v_fmamk_f32 v58, v58, 0x3e16c740, v100
	v_fmamk_f32 v59, v59, 0x3e16c740, v100
	v_fmamk_f32 v60, v60, 0x3e16c740, v100
	v_fmamk_f32 v61, v61, 0x3e16c740, v100
	v_fmamk_f32 v62, v62, 0x3e16c740, v100
	v_fmac_f32_e32 v101, 0x3e16c740, v63
	v_exp_f32_e32 v126, v48
	v_exp_f32_e32 v160, v49
	v_exp_f32_e32 v127, v50
	v_exp_f32_e32 v161, v51
	v_exp_f32_e32 v158, v52
	v_exp_f32_e32 v162, v53
	v_exp_f32_e32 v159, v54
	v_exp_f32_e32 v163, v55
	v_exp_f32_e32 v118, v56
	v_exp_f32_e32 v121, v57
	v_exp_f32_e32 v119, v58
	v_exp_f32_e32 v122, v59
	v_exp_f32_e32 v120, v60
	v_exp_f32_e32 v123, v61
	v_exp_f32_e32 v124, v62
	v_exp_f32_e32 v125, v101
	v_pk_fma_f32 v[114:115], v[32:33], s[40:41], v[100:101] op_sel_hi:[1,0,0]
	v_add_f32_e32 v32, v155, v156
	v_fmac_f32_e32 v32, v154, v142
	v_add_f32_e32 v142, v164, v165
	v_pk_fma_f32 v[112:113], v[34:35], s[40:41], v[100:101] op_sel_hi:[1,0,0]
	v_pk_fma_f32 v[108:109], v[36:37], s[40:41], v[100:101] op_sel_hi:[1,0,0]
	v_pk_fma_f32 v[104:105], v[38:39], s[40:41], v[100:101] op_sel_hi:[1,0,0]
	v_pk_fma_f32 v[102:103], v[40:41], s[40:41], v[100:101] op_sel_hi:[1,0,0]
	v_pk_fma_f32 v[110:111], v[42:43], s[40:41], v[100:101] op_sel_hi:[1,0,0]
	v_pk_fma_f32 v[106:107], v[44:45], s[40:41], v[100:101] op_sel_hi:[1,0,0]
	v_pk_fma_f32 v[100:101], v[46:47], s[40:41], v[100:101] op_sel_hi:[1,0,0]
	v_fmac_f32_e32 v142, v32, v157
	s_cbranch_vccz .Lmy_h2B_310
	s_and_saveexec_b64 s[12:13], s[4:5]
	ds_write_b32 v141, v117 offset:128
	s_or_b64 exec, exec, s[12:13]
	s_waitcnt lgkmcnt(0)
	ds_read_b128 v[192:195], v129 offset:224
	ds_read_b128 v[196:199], v129 offset:192
	ds_read_b128 v[200:203], v129 offset:160
	ds_read_b128 v[210:213], v129 offset:128
	s_waitcnt lgkmcnt(3)
	v_pk_mul_f32 v[14:15], v[14:15], v[194:195]
	s_waitcnt lgkmcnt(2)
	v_pk_mul_f32 v[10:11], v[10:11], v[198:199]
	s_waitcnt lgkmcnt(1)
	v_pk_mul_f32 v[6:7], v[6:7], v[202:203]
	s_waitcnt lgkmcnt(0)
	v_pk_mul_f32 v[2:3], v[2:3], v[212:213]
	v_pk_mul_f32 v[12:13], v[12:13], v[192:193]
	v_pk_mul_f32 v[8:9], v[8:9], v[196:197]
	v_pk_mul_f32 v[4:5], v[4:5], v[200:201]
	v_pk_mul_f32 v[0:1], v[0:1], v[210:211]
	v_pk_mul_f32 v[30:31], v[30:31], v[194:195]
	v_pk_mul_f32 v[26:27], v[26:27], v[198:199]
	v_pk_mul_f32 v[22:23], v[22:23], v[202:203]
	v_pk_mul_f32 v[18:19], v[18:19], v[212:213]
	v_pk_mul_f32 v[28:29], v[28:29], v[192:193]
	v_pk_mul_f32 v[24:25], v[24:25], v[196:197]
	v_pk_mul_f32 v[20:21], v[20:21], v[200:201]
	v_pk_mul_f32 v[16:17], v[16:17], v[210:211]
